# v025 + 64-byte alignment of the 18 MFMA loop headers (GEMM K-loops, attention tile loops)
# speedup vs baseline: 1.0049x; 1.0049x over previous
.LBB0_250:
	s_waitcnt lgkmcnt(0)
	s_barrier
	s_setprio 1
	s_waitcnt lgkmcnt(0)
	v_mfma_f32_16x16x128_f8f6f4 v[126:129], v[26:33], v[58:65], v[126:129]
	v_mfma_f32_16x16x128_f8f6f4 v[122:125], v[18:25], v[58:65], v[122:125]
	v_mfma_f32_16x16x128_f8f6f4 v[110:113], v[26:33], v[50:57], v[110:113]
	v_mfma_f32_16x16x128_f8f6f4 v[106:109], v[18:25], v[50:57], v[106:109]
	v_mfma_f32_16x16x128_f8f6f4 v[94:97], v[26:33], v[42:49], v[94:97]
	v_mfma_f32_16x16x128_f8f6f4 v[90:93], v[18:25], v[42:49], v[90:93]
	v_mfma_f32_16x16x128_f8f6f4 v[78:81], v[26:33], v[34:41], v[78:81]
	v_mfma_f32_16x16x128_f8f6f4 v[74:77], v[18:25], v[34:41], v[74:77]
	s_setprio 0
	s_setprio 1
	v_mfma_f32_16x16x128_f8f6f4 v[118:121], v[10:17], v[58:65], v[118:121]
	v_mfma_f32_16x16x128_f8f6f4 v[114:117], v[2:9], v[58:65], v[114:117]
	v_mfma_f32_16x16x128_f8f6f4 v[102:105], v[10:17], v[50:57], v[102:105]
	v_mfma_f32_16x16x128_f8f6f4 v[98:101], v[2:9], v[50:57], v[98:101]
	v_mfma_f32_16x16x128_f8f6f4 v[86:89], v[10:17], v[42:49], v[86:89]
	v_mfma_f32_16x16x128_f8f6f4 v[82:85], v[2:9], v[42:49], v[82:85]
	v_mfma_f32_16x16x128_f8f6f4 v[70:73], v[10:17], v[34:41], v[70:73]
	v_mfma_f32_16x16x128_f8f6f4 v[66:69], v[2:9], v[34:41], v[66:69]
	s_setprio 0
	s_barrier
	v_add_u32_e32 v14, s53, v205
	v_add_u32_e32 v30, s58, v205
	ds_read_b128 v[2:5], v14
	ds_read_b128 v[6:9], v14 offset:1024
	ds_read_b128 v[10:13], v14 offset:2048
	ds_read_b128 v[14:17], v14 offset:3072
	ds_read_b128 v[18:21], v30
	ds_read_b128 v[22:25], v30 offset:1024
	ds_read_b128 v[26:29], v30 offset:2048
	ds_read_b128 v[30:33], v30 offset:3072
	s_add_u32 s36, s36, 0x530000
	s_addc_u32 s37, s37, 0
	s_mov_b32 m0, s51
	v_lshl_add_u64 v[242:243], s[36:37], 0, v[194:195]
	ds_read_b128 v[34:37], v234 offset:32768
	ds_read_b128 v[38:41], v234 offset:33792
	ds_read_b128 v[42:45], v234 offset:34816
	ds_read_b128 v[46:49], v234 offset:35840
	ds_read_b128 v[50:53], v234 offset:36864
	ds_read_b128 v[54:57], v234 offset:37888
	ds_read_b128 v[58:61], v234 offset:38912
	ds_read_b128 v[62:65], v234 offset:39936
	global_load_lds_dwordx4 v[242:243], off
	v_lshl_add_u64 v[242:243], s[36:37], 0, v[198:199]
	s_mov_b32 m0, s52
	s_nop 0
	global_load_lds_dwordx4 v[242:243], off
	s_waitcnt vmcnt(8)
	s_waitcnt lgkmcnt(0)
	s_barrier
	s_setprio 1
	s_waitcnt lgkmcnt(0)
	v_mfma_f32_16x16x128_f8f6f4 v[190:193], v[2:9], v[34:41], v[190:193]
	v_mfma_f32_16x16x128_f8f6f4 v[186:189], v[10:17], v[34:41], v[186:189]
	v_mfma_f32_16x16x128_f8f6f4 v[174:177], v[2:9], v[42:49], v[174:177]
	v_mfma_f32_16x16x128_f8f6f4 v[170:173], v[10:17], v[42:49], v[170:173]
	v_mfma_f32_16x16x128_f8f6f4 v[158:161], v[2:9], v[50:57], v[158:161]
	v_mfma_f32_16x16x128_f8f6f4 v[154:157], v[10:17], v[50:57], v[154:157]
	v_mfma_f32_16x16x128_f8f6f4 v[142:145], v[2:9], v[58:65], v[142:145]
	v_mfma_f32_16x16x128_f8f6f4 v[138:141], v[10:17], v[58:65], v[138:141]
	s_setprio 0
	s_setprio 1
	v_mfma_f32_16x16x128_f8f6f4 v[182:185], v[18:25], v[34:41], v[182:185]
	v_mfma_f32_16x16x128_f8f6f4 v[178:181], v[26:33], v[34:41], v[178:181]
	v_mfma_f32_16x16x128_f8f6f4 v[166:169], v[18:25], v[42:49], v[166:169]
	v_mfma_f32_16x16x128_f8f6f4 v[162:165], v[26:33], v[42:49], v[162:165]
	v_mfma_f32_16x16x128_f8f6f4 v[150:153], v[18:25], v[50:57], v[150:153]
	v_mfma_f32_16x16x128_f8f6f4 v[146:149], v[26:33], v[50:57], v[146:149]
	v_mfma_f32_16x16x128_f8f6f4 v[134:137], v[18:25], v[58:65], v[134:137]
	v_mfma_f32_16x16x128_f8f6f4 v[130:133], v[26:33], v[58:65], v[130:133]
	s_setprio 0
	s_barrier
	s_mov_b32 m0, s54
	v_lshl_add_u64 v[222:223], v[222:223], 0, s[12:13]
	s_add_u32 s34, s34, 0x40080
	ds_read_b128 v[34:37], v234 offset:49152
	ds_read_b128 v[38:41], v234 offset:50176
	ds_read_b128 v[42:45], v234 offset:51200
	ds_read_b128 v[46:49], v234 offset:52224
	ds_read_b128 v[50:53], v234 offset:53248
	ds_read_b128 v[54:57], v234 offset:54272
	ds_read_b128 v[58:61], v234 offset:55296
	ds_read_b128 v[62:65], v234 offset:56320
	global_load_lds_dwordx4 v[222:223], off
	v_lshl_add_u64 v[222:223], v[224:225], 0, s[12:13]
	s_mov_b32 m0, s55
	s_addc_u32 s35, s35, 0
	global_load_lds_dwordx4 v[222:223], off
	v_lshl_add_u64 v[222:223], s[34:35], 0, v[196:197]
	s_mov_b32 m0, s59
	s_nop 0
	global_load_lds_dwordx4 v[222:223], off
	v_lshl_add_u64 v[222:223], s[34:35], 0, v[200:201]
	s_mov_b32 m0, s60
	s_nop 0
	global_load_lds_dwordx4 v[222:223], off
	v_lshl_add_u64 v[222:223], v[226:227], 0, s[12:13]
	s_mov_b32 m0, s56
	s_nop 0
	global_load_lds_dwordx4 v[222:223], off
	v_lshl_add_u64 v[222:223], v[228:229], 0, s[12:13]
	s_mov_b32 m0, s57
	s_nop 0
	global_load_lds_dwordx4 v[222:223], off
	s_waitcnt vmcnt(8)
	s_waitcnt lgkmcnt(0)
	s_barrier
	s_setprio 1
	s_waitcnt lgkmcnt(0)
	v_mfma_f32_16x16x128_f8f6f4 v[126:129], v[2:9], v[34:41], v[126:129]
	v_mfma_f32_16x16x128_f8f6f4 v[122:125], v[10:17], v[34:41], v[122:125]
	v_mfma_f32_16x16x128_f8f6f4 v[110:113], v[2:9], v[42:49], v[110:113]
	v_mfma_f32_16x16x128_f8f6f4 v[106:109], v[10:17], v[42:49], v[106:109]
	v_mfma_f32_16x16x128_f8f6f4 v[94:97], v[2:9], v[50:57], v[94:97]
	v_mfma_f32_16x16x128_f8f6f4 v[90:93], v[10:17], v[50:57], v[90:93]
	v_mfma_f32_16x16x128_f8f6f4 v[78:81], v[2:9], v[58:65], v[78:81]
	v_mfma_f32_16x16x128_f8f6f4 v[74:77], v[10:17], v[58:65], v[74:77]
	s_setprio 0
	s_setprio 1
	v_mfma_f32_16x16x128_f8f6f4 v[118:121], v[18:25], v[34:41], v[118:121]
	v_mfma_f32_16x16x128_f8f6f4 v[114:117], v[26:33], v[34:41], v[114:117]
	v_mfma_f32_16x16x128_f8f6f4 v[102:105], v[18:25], v[42:49], v[102:105]
	v_mfma_f32_16x16x128_f8f6f4 v[98:101], v[26:33], v[42:49], v[98:101]
	v_mfma_f32_16x16x128_f8f6f4 v[86:89], v[18:25], v[50:57], v[86:89]
	v_mfma_f32_16x16x128_f8f6f4 v[82:85], v[26:33], v[50:57], v[82:85]
	v_mfma_f32_16x16x128_f8f6f4 v[70:73], v[18:25], v[58:65], v[70:73]
	v_mfma_f32_16x16x128_f8f6f4 v[66:69], v[26:33], v[58:65], v[66:69]
	s_setprio 0
	s_barrier
	s_add_i32 s80, s80, 2
	s_add_u32 s30, s30, 0x100
	s_addc_u32 s31, s31, 0
	s_cmp_gt_u32 s80, 13
	s_cbranch_scc1 .LBB0_258
	.p2align 6

.LBB0_506:
	s_waitcnt vmcnt(0)
	v_lshlrev_b32_e32 v58, 16, v46
	v_and_b32_e32 v46, 0xffff0000, v46
	v_mov_b32_e32 v146, v171
	v_cvt_pk_fp8_f32 v146, v58, v46
	v_lshlrev_b32_e32 v58, 16, v48
	v_and_b32_e32 v48, 0xffff0000, v48
	v_mov_b32_e32 v147, v171
	v_cvt_pk_fp8_f32 v147, v58, v48
	v_lshlrev_b32_e32 v46, 16, v47
	v_and_b32_e32 v47, 0xffff0000, v47
	v_cvt_pk_fp8_f32 v146, v46, v47 op_sel:[0,0,1]
	v_lshlrev_b32_e32 v46, 16, v49
	v_and_b32_e32 v47, 0xffff0000, v49
	v_cvt_pk_fp8_f32 v147, v46, v47 op_sel:[0,0,1]
	v_lshlrev_b32_e32 v46, 16, v42
	v_and_b32_e32 v42, 0xffff0000, v42
	v_mov_b32_e32 v148, v171
	v_cvt_pk_fp8_f32 v148, v46, v42
	v_lshlrev_b32_e32 v46, 16, v44
	v_and_b32_e32 v44, 0xffff0000, v44
	v_mov_b32_e32 v149, v171
	v_cvt_pk_fp8_f32 v149, v46, v44
	v_lshlrev_b32_e32 v42, 16, v43
	v_and_b32_e32 v43, 0xffff0000, v43
	v_cvt_pk_fp8_f32 v148, v42, v43 op_sel:[0,0,1]
	v_lshlrev_b32_e32 v42, 16, v45
	v_and_b32_e32 v43, 0xffff0000, v45
	v_cvt_pk_fp8_f32 v149, v42, v43 op_sel:[0,0,1]
	v_lshlrev_b32_e32 v42, 16, v38
	v_and_b32_e32 v38, 0xffff0000, v38
	v_mov_b32_e32 v150, v171
	v_cvt_pk_fp8_f32 v150, v42, v38
	v_lshlrev_b32_e32 v42, 16, v40
	v_and_b32_e32 v40, 0xffff0000, v40
	v_mov_b32_e32 v151, v171
	v_cvt_pk_fp8_f32 v151, v42, v40
	v_lshlrev_b32_e32 v38, 16, v39
	v_and_b32_e32 v39, 0xffff0000, v39
	v_cvt_pk_fp8_f32 v150, v38, v39 op_sel:[0,0,1]
	v_lshlrev_b32_e32 v38, 16, v41
	v_and_b32_e32 v39, 0xffff0000, v41
	v_cvt_pk_fp8_f32 v151, v38, v39 op_sel:[0,0,1]
	v_lshlrev_b32_e32 v38, 16, v34
	v_and_b32_e32 v34, 0xffff0000, v34
	v_mov_b32_e32 v152, v171
	v_cvt_pk_fp8_f32 v152, v38, v34
	v_lshlrev_b32_e32 v38, 16, v36
	v_and_b32_e32 v36, 0xffff0000, v36
	v_mov_b32_e32 v153, v171
	v_cvt_pk_fp8_f32 v153, v38, v36
	v_lshlrev_b32_e32 v34, 16, v35
	v_and_b32_e32 v35, 0xffff0000, v35
	v_cvt_pk_fp8_f32 v152, v34, v35 op_sel:[0,0,1]
	v_lshlrev_b32_e32 v34, 16, v37
	v_and_b32_e32 v35, 0xffff0000, v37
	v_cvt_pk_fp8_f32 v153, v34, v35 op_sel:[0,0,1]
	v_lshlrev_b32_e32 v34, 16, v30
	v_and_b32_e32 v30, 0xffff0000, v30
	v_mov_b32_e32 v154, v171
	v_cvt_pk_fp8_f32 v154, v34, v30
	v_lshlrev_b32_e32 v34, 16, v32
	v_and_b32_e32 v32, 0xffff0000, v32
	v_mov_b32_e32 v155, v171
	v_cvt_pk_fp8_f32 v155, v34, v32
	v_lshlrev_b32_e32 v30, 16, v31
	v_and_b32_e32 v31, 0xffff0000, v31
	v_cvt_pk_fp8_f32 v154, v30, v31 op_sel:[0,0,1]
	v_lshlrev_b32_e32 v30, 16, v33
	v_and_b32_e32 v31, 0xffff0000, v33
	v_cvt_pk_fp8_f32 v155, v30, v31 op_sel:[0,0,1]
	v_lshlrev_b32_e32 v30, 16, v26
	v_and_b32_e32 v26, 0xffff0000, v26
	v_mov_b32_e32 v156, v171
	v_cvt_pk_fp8_f32 v156, v30, v26
	v_lshlrev_b32_e32 v30, 16, v28
	v_and_b32_e32 v28, 0xffff0000, v28
	v_mov_b32_e32 v157, v171
	v_cvt_pk_fp8_f32 v157, v30, v28
	v_lshlrev_b32_e32 v26, 16, v27
	v_and_b32_e32 v27, 0xffff0000, v27
	v_cvt_pk_fp8_f32 v156, v26, v27 op_sel:[0,0,1]
	v_lshlrev_b32_e32 v26, 16, v29
	v_and_b32_e32 v27, 0xffff0000, v29
	v_cvt_pk_fp8_f32 v157, v26, v27 op_sel:[0,0,1]
	v_lshlrev_b32_e32 v26, 16, v22
	v_and_b32_e32 v22, 0xffff0000, v22
	v_mov_b32_e32 v158, v171
	v_cvt_pk_fp8_f32 v158, v26, v22
	v_lshlrev_b32_e32 v26, 16, v24
	v_and_b32_e32 v24, 0xffff0000, v24
	v_mov_b32_e32 v159, v171
	v_cvt_pk_fp8_f32 v159, v26, v24
	v_lshlrev_b32_e32 v22, 16, v23
	v_and_b32_e32 v23, 0xffff0000, v23
	v_cvt_pk_fp8_f32 v158, v22, v23 op_sel:[0,0,1]
	v_lshlrev_b32_e32 v22, 16, v25
	v_and_b32_e32 v23, 0xffff0000, v25
	v_cvt_pk_fp8_f32 v159, v22, v23 op_sel:[0,0,1]
	v_lshlrev_b32_e32 v22, 16, v18
	v_and_b32_e32 v18, 0xffff0000, v18
	v_mov_b32_e32 v160, v171
	v_cvt_pk_fp8_f32 v160, v22, v18
	v_lshlrev_b32_e32 v22, 16, v20
	v_and_b32_e32 v20, 0xffff0000, v20
	v_mov_b32_e32 v161, v171
	v_cvt_pk_fp8_f32 v161, v22, v20
	v_lshlrev_b32_e32 v18, 16, v19
	v_and_b32_e32 v19, 0xffff0000, v19
	v_cvt_pk_fp8_f32 v160, v18, v19 op_sel:[0,0,1]
	v_lshlrev_b32_e32 v18, 16, v21
	v_and_b32_e32 v19, 0xffff0000, v21
	v_cvt_pk_fp8_f32 v161, v18, v19 op_sel:[0,0,1]
	v_lshlrev_b32_e32 v18, 16, v14
	v_and_b32_e32 v14, 0xffff0000, v14
	v_mov_b32_e32 v162, v171
	v_cvt_pk_fp8_f32 v162, v18, v14
	v_lshlrev_b32_e32 v18, 16, v16
	v_and_b32_e32 v16, 0xffff0000, v16
	v_mov_b32_e32 v163, v171
	v_cvt_pk_fp8_f32 v163, v18, v16
	v_lshlrev_b32_e32 v14, 16, v15
	v_and_b32_e32 v15, 0xffff0000, v15
	v_cvt_pk_fp8_f32 v162, v14, v15 op_sel:[0,0,1]
	v_lshlrev_b32_e32 v14, 16, v17
	v_and_b32_e32 v15, 0xffff0000, v17
	v_cvt_pk_fp8_f32 v163, v14, v15 op_sel:[0,0,1]
	v_lshlrev_b32_e32 v14, 16, v10
	v_and_b32_e32 v10, 0xffff0000, v10
	v_mov_b32_e32 v164, v171
	v_cvt_pk_fp8_f32 v164, v14, v10
	v_lshlrev_b32_e32 v14, 16, v12
	v_and_b32_e32 v12, 0xffff0000, v12
	v_mov_b32_e32 v165, v171
	v_cvt_pk_fp8_f32 v165, v14, v12
	v_lshlrev_b32_e32 v10, 16, v11
	v_and_b32_e32 v11, 0xffff0000, v11
	v_cvt_pk_fp8_f32 v164, v10, v11 op_sel:[0,0,1]
	v_lshlrev_b32_e32 v10, 16, v13
	v_and_b32_e32 v11, 0xffff0000, v13
	v_cvt_pk_fp8_f32 v165, v10, v11 op_sel:[0,0,1]
	v_lshlrev_b32_e32 v10, 16, v6
	v_and_b32_e32 v6, 0xffff0000, v6
	v_mov_b32_e32 v166, v171
	v_cvt_pk_fp8_f32 v166, v10, v6
	v_lshlrev_b32_e32 v10, 16, v8
	v_and_b32_e32 v8, 0xffff0000, v8
	v_mov_b32_e32 v167, v171
	v_cvt_pk_fp8_f32 v167, v10, v8
	v_lshlrev_b32_e32 v6, 16, v7
	v_and_b32_e32 v7, 0xffff0000, v7
	v_cvt_pk_fp8_f32 v166, v6, v7 op_sel:[0,0,1]
	v_lshlrev_b32_e32 v6, 16, v9
	v_and_b32_e32 v7, 0xffff0000, v9
	v_cvt_pk_fp8_f32 v167, v6, v7 op_sel:[0,0,1]
	v_lshlrev_b32_e32 v6, 16, v2
	v_and_b32_e32 v2, 0xffff0000, v2
	v_mov_b32_e32 v168, v171
	v_cvt_pk_fp8_f32 v168, v6, v2
	v_lshlrev_b32_e32 v6, 16, v4
	v_and_b32_e32 v4, 0xffff0000, v4
	v_mov_b32_e32 v169, v171
	v_cvt_pk_fp8_f32 v169, v6, v4
	v_lshlrev_b32_e32 v2, 16, v3
	v_and_b32_e32 v3, 0xffff0000, v3
	v_cvt_pk_fp8_f32 v168, v2, v3 op_sel:[0,0,1]
	v_lshlrev_b32_e32 v2, 16, v5
	v_and_b32_e32 v3, 0xffff0000, v5
	v_cvt_pk_fp8_f32 v169, v2, v3 op_sel:[0,0,1]
	v_lshrrev_b32_e32 v2, 1, v55
	v_and_b32_e32 v3, 8, v55
	v_and_or_b32 v2, v2, 3, v3
	v_bfe_u32 v58, v55, 5, 1
	v_lshlrev_b32_e32 v2, 7, v2
	v_lshl_or_b32 v10, v58, 9, v2
	v_lshlrev_b32_e32 v2, 3, v55
	v_lshlrev_b32_e32 v42, 3, v52
	v_or_b32_e32 v61, 32, v52
	v_and_b32_e32 v11, 8, v2
	s_waitcnt lgkmcnt(0)
	v_bitop3_b32 v12, v42, v56, s45 bitop3:0x6c
	v_lshl_add_u32 v43, v52, 7, s63
	v_or_b32_e32 v2, 16, v56
	v_lshl_add_u32 v44, v61, 7, s63
	s_barrier
	v_add_u32_e32 v213, v43, v12
	v_bitop3_b32 v13, v42, v2, s45 bitop3:0x6c
	v_add_u32_e32 v215, v44, v12
	v_add_u32_e32 v214, v43, v13
	ds_read_b128 v[2:5], v213 offset:32768
	ds_read_b128 v[6:9], v214 offset:32768
	v_add_u32_e32 v216, v44, v13
	ds_read_b128 v[34:37], v215 offset:32768
	ds_read_b128 v[38:41], v216 offset:32768
	v_bfe_u32 v59, v55, 1, 3
	v_add3_u32 v62, v11, s63, v10
	v_bitop3_b32 v10, v57, v59, 1 bitop3:0x6c
	v_lshl_add_u32 v208, v10, 4, v62
	s_waitcnt lgkmcnt(0)
	v_mfma_f32_32x32x64_f8f6f4 v[18:33], v[2:9], v[146:153], 0
	v_mfma_f32_32x32x64_f8f6f4 v[2:17], v[34:41], v[146:153], 0
	v_or_b32_e32 v34, 64, v56
	v_bitop3_b32 v45, v42, v34, s45 bitop3:0x6c
	v_or_b32_e32 v34, 0x50, v56
	v_add_u32_e32 v217, v43, v45
	v_bitop3_b32 v42, v42, v34, s45 bitop3:0x6c
	v_add_u32_e32 v218, v43, v42
	ds_read_b128 v[34:37], v217 offset:32768
	ds_read_b128 v[38:41], v218 offset:32768
	v_add_u32_e32 v211, v44, v45
	v_add_u32_e32 v212, v44, v42
	ds_read_b128 v[42:45], v211 offset:32768
	ds_read_b128 v[46:49], v212 offset:32768
	s_waitcnt lgkmcnt(2)
	v_mfma_f32_32x32x64_f8f6f4 v[18:33], v[34:41], v[154:161], v[18:33]
	v_lshlrev_b32_e32 v34, 1, v58
	v_lshrrev_b32_e32 v35, 2, v55
	v_and_b32_e32 v199, 63, v55
	v_and_b32_e32 v60, 1, v57
	v_lshlrev_b32_e32 v57, 6, v52
	v_bfe_u32 v36, v55, 2, 2
	v_bitop3_b32 v35, v34, v35, 3 bitop3:0x78
	v_lshlrev_b32_e32 v55, 6, v61
	s_waitcnt lgkmcnt(0)
	v_mfma_f32_32x32x64_f8f6f4 v[2:17], v[42:49], v[154:161], v[2:17]
	v_lshlrev_b32_e32 v219, 4, v35
	v_add_u32_e32 v35, s37, v57
	v_bitop3_b32 v34, v34, v36, 1 bitop3:0x36
	v_add_u32_e32 v42, s37, v55
	v_add_u32_e32 v220, v35, v219
	v_lshlrev_b32_e32 v221, 4, v34
	v_add_u32_e32 v223, v42, v219
	v_add_u32_e32 v222, v35, v221
	ds_read_b128 v[34:37], v220
	ds_read_b128 v[38:41], v222
	v_add_u32_e32 v224, v42, v221
	ds_read_b128 v[42:45], v223
	ds_read_b128 v[46:49], v224
	s_waitcnt lgkmcnt(2)
	v_mfma_f32_32x32x64_f8f6f4 v[18:33], v[34:41], v[162:169], v[18:33]
	s_waitcnt lgkmcnt(0)
	v_mfma_f32_32x32x64_f8f6f4 v[2:17], v[42:49], v[162:169], v[2:17]
	s_nop 0
	s_nop 15
	s_nop 7
	s_and_b32 s2, s54, 0x3fffffc0
	v_max_f32_e32 v34, v19, v19
	v_max_f32_e32 v35, v18, v18
	v_max_f32_e32 v34, v35, v34
	v_max3_f32 v34, v34, v20, v21
	v_max3_f32 v34, v34, v22, v23
	v_max3_f32 v34, v34, v24, v25
	v_max3_f32 v34, v34, v26, v27
	v_max3_f32 v34, v34, v28, v29
	v_max3_f32 v34, v34, v30, v31
	v_max3_f32 v34, v34, v32, v33
	v_max3_f32 v34, v34, v2, v3
	v_max3_f32 v34, v34, v4, v5
	v_max3_f32 v34, v34, v6, v7
	v_max3_f32 v34, v34, v8, v9
	v_max3_f32 v34, v34, v10, v11
	v_max3_f32 v34, v34, v12, v13
	v_max3_f32 v34, v34, v14, v15
	v_max3_f32 v34, v34, v16, v17
	v_mov_b32_e32 v35, v34
	s_nop 1
	v_permlane32_swap_b32_e32 v34, v35
	v_max_f32_e32 v35, v35, v35
	v_max_f32_e32 v34, v34, v34
	v_max_f32_e32 v34, v34, v35
	s_lshl_b32 s2, s2, 2
	v_add_f32_e32 v35, 0x7149f2ca, v34
	s_add_i32 s54, s36, s2
	v_cmp_ge_f32_e32 vcc, s46, v35
	s_cmp_eq_u64 vcc, exec
	v_max_f32_e32 v34, 0xf149f2ca, v34
	s_cselect_b64 vcc, -1, 0
	v_cndmask_b32_e32 v233, v34, v198, vcc
	v_sub_f32_e32 v36, 0xf149f2ca, v34
	v_fma_f32 v34, v233, s47, 4.0
	v_mov_b32_e32 v35, v34
	s_add_u32 s2, s26, s28
	v_fmac_f32_e32 v35, 0x3dd53b94, v33
	s_addc_u32 s3, s27, s29
	s_add_i32 s55, s63, s55
	v_pk_fma_f32 v[66:67], v[2:3], s[6:7], v[34:35] op_sel_hi:[1,0,0]
	v_lshl_add_u64 v[2:3], s[2:3], 0, v[174:175]
	s_add_i32 s58, s55, 0x4000
	v_lshl_add_u64 v[2:3], v[2:3], 0, s[8:9]
	s_mov_b32 m0, s58
	v_lshl_add_u64 v[176:177], s[24:25], 0, v[172:173]
	global_load_lds_dwordx4 v[2:3], off
	s_add_u32 s24, s40, s53
	s_addc_u32 s25, s41, 0
	s_add_u32 s24, s24, s28
	v_mul_f32_e32 v36, 0x3dd53b94, v36
	s_addc_u32 s25, s25, s29
	v_bitop3_b32 v56, v60, v59, 2 bitop3:0x36
	v_exp_f32_e32 v36, v36
	v_fmamk_f32 v18, v18, 0x3dd53b94, v34
	v_fmamk_f32 v19, v19, 0x3dd53b94, v34
	v_fmamk_f32 v20, v20, 0x3dd53b94, v34
	v_fmamk_f32 v21, v21, 0x3dd53b94, v34
	v_fmamk_f32 v22, v22, 0x3dd53b94, v34
	v_fmamk_f32 v23, v23, 0x3dd53b94, v34
	v_fmamk_f32 v24, v24, 0x3dd53b94, v34
	v_fmamk_f32 v25, v25, 0x3dd53b94, v34
	v_fmamk_f32 v26, v26, 0x3dd53b94, v34
	v_fmamk_f32 v27, v27, 0x3dd53b94, v34
	v_fmamk_f32 v28, v28, 0x3dd53b94, v34
	v_fmamk_f32 v29, v29, 0x3dd53b94, v34
	v_fmamk_f32 v30, v30, 0x3dd53b94, v34
	v_fmamk_f32 v31, v31, 0x3dd53b94, v34
	v_fmamk_f32 v32, v32, 0x3dd53b94, v34
	v_lshl_add_u64 v[184:185], s[24:25], 0, v[174:175]
	s_add_u32 s24, s28, s53
	v_lshl_add_u32 v210, v56, 4, v62
	v_bitop3_b32 v56, v60, v59, 4 bitop3:0x36
	v_exp_f32_e32 v82, v18
	v_exp_f32_e32 v83, v19
	v_exp_f32_e32 v84, v20
	v_exp_f32_e32 v85, v21
	v_exp_f32_e32 v190, v22
	v_exp_f32_e32 v191, v23
	v_exp_f32_e32 v188, v24
	v_exp_f32_e32 v189, v25
	v_exp_f32_e32 v144, v26
	v_exp_f32_e32 v145, v27
	v_exp_f32_e32 v138, v28
	v_exp_f32_e32 v139, v29
	v_exp_f32_e32 v142, v30
	v_exp_f32_e32 v143, v31
	v_exp_f32_e32 v140, v32
	v_exp_f32_e32 v141, v35
	s_waitcnt vmcnt(1)
	v_lshl_add_u64 v[2:3], s[4:5], 0, v[50:51]
	s_addc_u32 s25, s29, 0
	v_lshl_add_u32 v209, v56, 4, v62
	v_bitop3_b32 v56, v60, v59, 6 bitop3:0x36
	s_barrier
	v_lshl_add_u64 v[182:183], v[2:3], 0, v[170:171]
	v_add_u32_e32 v2, v54, v53
	s_add_u32 s24, s42, s24
	v_lshl_add_u32 v206, v56, 4, v62
	v_ashrrev_i32_e32 v3, 31, v2
	s_addc_u32 s25, s43, s25
	v_mov_b32_e32 v200, 0
	s_mov_b32 s23, 2
	v_cndmask_b32_e64 v225, v36, 1.0, vcc
	v_pk_fma_f32 v[80:81], v[16:17], s[6:7], v[34:35] op_sel_hi:[1,0,0]
	v_pk_fma_f32 v[78:79], v[14:15], s[6:7], v[34:35] op_sel_hi:[1,0,0]
	v_pk_fma_f32 v[76:77], v[12:13], s[6:7], v[34:35] op_sel_hi:[1,0,0]
	v_pk_fma_f32 v[74:75], v[10:11], s[6:7], v[34:35] op_sel_hi:[1,0,0]
	v_pk_fma_f32 v[72:73], v[8:9], s[6:7], v[34:35] op_sel_hi:[1,0,0]
	v_pk_fma_f32 v[70:71], v[6:7], s[6:7], v[34:35] op_sel_hi:[1,0,0]
	v_pk_fma_f32 v[68:69], v[4:5], s[6:7], v[34:35] op_sel_hi:[1,0,0]
	v_add_u32_e32 v226, s38, v57
	v_add_u32_e32 v227, s38, v55
	v_cmp_gt_u32_e64 s[2:3], 32, v199
	v_lshl_add_u32 v207, v52, 2, s54
	v_lshl_add_u32 v205, v58, 4, s54
	v_add_u32_e32 v204, 0x4000, v208
	v_add_u32_e32 v203, 0x4000, v210
	v_add_u32_e32 v202, 0x4000, v209
	v_add_u32_e32 v201, 0x4000, v206
	v_lshl_add_u64 v[178:179], s[0:1], 0, v[170:171]
	v_lshl_add_u64 v[180:181], s[26:27], 0, v[174:175]
	v_lshl_add_u64 v[186:187], s[24:25], 0, v[2:3]
	s_movk_i32 s28, 0xc0
	v_mov_b32_e32 v2, 0
	v_mov_b32_e32 v3, v200
	v_mov_b32_e32 v4, v200
	v_mov_b32_e32 v5, v200
	v_mov_b32_e32 v6, v200
	v_mov_b32_e32 v7, v200
	v_mov_b32_e32 v8, v200
	v_mov_b32_e32 v9, v200
	v_mov_b32_e32 v10, v200
	v_mov_b32_e32 v11, v200
	v_mov_b32_e32 v12, v200
	v_mov_b32_e32 v13, v200
	v_mov_b32_e32 v14, v200
	v_mov_b32_e32 v15, v200
	v_mov_b32_e32 v16, v200
	v_mov_b32_e32 v17, v200
	v_mov_b32_e32 v18, 0
	v_mov_b32_e32 v19, v200
	v_mov_b32_e32 v20, v200
	v_mov_b32_e32 v21, v200
	v_mov_b32_e32 v22, v200
	v_mov_b32_e32 v23, v200
	v_mov_b32_e32 v24, v200
	v_mov_b32_e32 v25, v200
	v_mov_b32_e32 v26, v200
	v_mov_b32_e32 v27, v200
	v_mov_b32_e32 v28, v200
	v_mov_b32_e32 v29, v200
	v_mov_b32_e32 v30, v200
	v_mov_b32_e32 v31, v200
	v_mov_b32_e32 v32, v200
	v_mov_b32_e32 v33, v200
	v_mov_b32_e32 v34, 0
	v_mov_b32_e32 v35, v200
	v_mov_b32_e32 v36, v200
	v_mov_b32_e32 v37, v200
	v_mov_b32_e32 v38, v200
	v_mov_b32_e32 v39, v200
	v_mov_b32_e32 v40, v200
	v_mov_b32_e32 v41, v200
	v_mov_b32_e32 v42, v200
	v_mov_b32_e32 v43, v200
	v_mov_b32_e32 v44, v200
	v_mov_b32_e32 v45, v200
	v_mov_b32_e32 v46, v200
	v_mov_b32_e32 v47, v200
	v_mov_b32_e32 v48, v200
	v_mov_b32_e32 v49, v200
	v_mov_b32_e32 v50, 0
	v_mov_b32_e32 v51, v200
	v_mov_b32_e32 v52, v200
	v_mov_b32_e32 v53, v200
	v_mov_b32_e32 v54, v200
	v_mov_b32_e32 v55, v200
	v_mov_b32_e32 v56, v200
	v_mov_b32_e32 v57, v200
	v_mov_b32_e32 v58, v200
	v_mov_b32_e32 v59, v200
	v_mov_b32_e32 v60, v200
	v_mov_b32_e32 v61, v200
	v_mov_b32_e32 v62, v200
	v_mov_b32_e32 v63, v200
	v_mov_b32_e32 v64, v200
	v_mov_b32_e32 v65, v200
	.p2align 6

.LBB0_550:
	v_lshrrev_b32_e32 v4, 3, v39
	v_and_b32_e32 v3, 8, v39
	v_and_b32_e32 v58, 4, v4
	v_bfe_u32 v4, v39, 1, 2
	v_or3_b32 v3, v4, v3, v58
	v_lshlrev_b32_e32 v4, 3, v39
	v_bfe_u32 v56, v39, 1, 3
	v_lshlrev_b32_e32 v3, 7, v3
	v_and_b32_e32 v4, 8, v4
	v_and_b32_e32 v57, 1, v2
	v_add3_u32 v59, v4, s63, v3
	v_bitop3_b32 v2, v2, v56, 1 bitop3:0x6c
	v_lshlrev_b32_e32 v48, 3, v38
	v_lshl_add_u32 v195, v2, 4, v59
	v_bitop3_b32 v2, v48, v162, s28 bitop3:0x6c
	v_lshl_add_u32 v49, v38, 7, s63
	s_waitcnt lgkmcnt(0)
	v_add_u32_e32 v199, v49, v2
	v_or_b32_e32 v2, 16, v162
	s_barrier
	v_bitop3_b32 v2, v48, v2, s28 bitop3:0x6c
	v_add_u32_e32 v200, v49, v2
	ds_read_b128 v[2:5], v199 offset:32768
	ds_read_b128 v[40:43], v199 offset:36864
	ds_read_b128 v[6:9], v200 offset:32768
	ds_read_b128 v[44:47], v200 offset:36864
	v_bitop3_b32 v10, v57, v56, 2 bitop3:0x36
	v_lshl_add_u32 v196, v10, 4, v59
	v_bitop3_b32 v10, v57, v56, 4 bitop3:0x36
	v_lshl_add_u32 v194, v10, 4, v59
	s_waitcnt vmcnt(0) lgkmcnt(0)
	v_mfma_f32_32x32x64_f8f6f4 v[18:33], v[2:9], v[154:161], 0
	v_mfma_f32_32x32x64_f8f6f4 v[2:17], v[40:47], v[154:161], 0
	v_or_b32_e32 v40, 64, v162
	v_bitop3_b32 v40, v48, v40, s28 bitop3:0x6c
	v_add_u32_e32 v197, v49, v40
	v_or_b32_e32 v40, 0x50, v162
	v_bitop3_b32 v40, v48, v40, s28 bitop3:0x6c
	v_add_u32_e32 v198, v49, v40
	ds_read_b128 v[40:43], v197 offset:32768
	ds_read_b128 v[48:51], v197 offset:36864
	ds_read_b128 v[44:47], v198 offset:32768
	ds_read_b128 v[52:55], v198 offset:36864
	s_waitcnt lgkmcnt(1)
	v_mfma_f32_32x32x64_f8f6f4 v[18:33], v[40:47], v[146:153], v[18:33]
	s_waitcnt lgkmcnt(0)
	v_mfma_f32_32x32x64_f8f6f4 v[2:17], v[48:55], v[146:153], v[2:17]
	v_and_b32_e32 v183, 63, v39
	s_nop 15
	s_nop 7
	s_and_b32 s24, s42, 0x3fffffc0
	v_max_f32_e32 v39, v19, v19
	v_max_f32_e32 v40, v18, v18
	v_max_f32_e32 v39, v40, v39
	v_max3_f32 v39, v39, v20, v21
	v_max3_f32 v39, v39, v22, v23
	v_max3_f32 v39, v39, v24, v25
	v_max3_f32 v39, v39, v26, v27
	v_max3_f32 v39, v39, v28, v29
	v_max3_f32 v39, v39, v30, v31
	v_max3_f32 v39, v39, v32, v33
	v_max3_f32 v39, v39, v2, v3
	v_max3_f32 v39, v39, v4, v5
	v_max3_f32 v39, v39, v6, v7
	v_max3_f32 v39, v39, v8, v9
	v_max3_f32 v39, v39, v10, v11
	v_max3_f32 v39, v39, v12, v13
	v_max3_f32 v39, v39, v14, v15
	v_max3_f32 v39, v39, v16, v17
	v_mov_b32_e32 v40, v39
	s_nop 1
	v_permlane32_swap_b32_e32 v39, v40
	v_max_f32_e32 v40, v40, v40
	v_max_f32_e32 v39, v39, v39
	v_max_f32_e32 v39, v39, v40
	v_add_f32_e32 v40, 0x7149f2ca, v39
	v_max_f32_e32 v39, 0xf149f2ca, v39
	s_lshl_b32 s24, s24, 2
	v_sub_f32_e32 v41, 0xf149f2ca, v39
	s_add_i32 s24, s5, s24
	v_mul_f32_e32 v41, 0x3e0293ee, v41
	v_cmp_ge_f32_e32 vcc, s29, v40
	v_exp_f32_e32 v41, v41
	s_cmp_eq_u64 vcc, exec
	s_cselect_b64 vcc, -1, 0
	s_add_u32 s2, s22, s2
	v_cndmask_b32_e32 v202, v39, v182, vcc
	s_addc_u32 s3, s23, s3
	s_add_i32 s25, s63, s43
	v_fma_f32 v40, v202, s33, 4.0
	s_add_i32 s43, s25, 0x4000
	v_pk_fma_f32 v[66:67], v[2:3], s[4:5], v[40:41] op_sel_hi:[1,0,0]
	v_lshl_add_u64 v[2:3], s[2:3], 0, v[36:37]
	s_mov_b32 m0, s43
	v_lshl_add_u64 v[168:169], v[36:37], 0, s[16:17]
	global_load_lds_dwordx4 v[2:3], off
	s_add_u32 s16, s39, 0x80
	s_addc_u32 s17, s45, 0
	v_mov_b32_e32 v39, v40
	v_lshl_add_u64 v[164:165], s[20:21], 0, v[34:35]
	s_mul_i32 s17, s41, s17
	s_mul_hi_u32 s20, s41, s16
	v_fmamk_f32 v18, v18, 0x3e0293ee, v40
	v_fmamk_f32 v19, v19, 0x3e0293ee, v40
	v_fmamk_f32 v20, v20, 0x3e0293ee, v40
	v_fmamk_f32 v21, v21, 0x3e0293ee, v40
	v_fmamk_f32 v22, v22, 0x3e0293ee, v40
	v_fmamk_f32 v23, v23, 0x3e0293ee, v40
	v_fmamk_f32 v24, v24, 0x3e0293ee, v40
	v_fmamk_f32 v25, v25, 0x3e0293ee, v40
	v_fmamk_f32 v26, v26, 0x3e0293ee, v40
	v_fmamk_f32 v27, v27, 0x3e0293ee, v40
	v_fmamk_f32 v28, v28, 0x3e0293ee, v40
	v_fmamk_f32 v29, v29, 0x3e0293ee, v40
	v_fmamk_f32 v30, v30, 0x3e0293ee, v40
	v_fmamk_f32 v31, v31, 0x3e0293ee, v40
	v_fmamk_f32 v32, v32, 0x3e0293ee, v40
	v_fmac_f32_e32 v39, 0x3e0293ee, v33
	s_add_i32 s20, s20, s17
	s_mul_i32 s16, s41, s16
	v_exp_f32_e32 v82, v18
	v_exp_f32_e32 v83, v19
	v_exp_f32_e32 v84, v20
	v_exp_f32_e32 v85, v21
	v_exp_f32_e32 v176, v22
	v_exp_f32_e32 v177, v23
	v_exp_f32_e32 v174, v24
	v_exp_f32_e32 v175, v25
	v_exp_f32_e32 v172, v26
	v_exp_f32_e32 v173, v27
	v_exp_f32_e32 v140, v28
	v_exp_f32_e32 v141, v29
	v_exp_f32_e32 v144, v30
	v_exp_f32_e32 v145, v31
	v_exp_f32_e32 v142, v32
	v_exp_f32_e32 v143, v39
	s_waitcnt vmcnt(1)
	s_add_u32 s16, s16, s44
	v_bitop3_b32 v56, v57, v56, 6 bitop3:0x36
	s_barrier
	s_addc_u32 s17, s20, 0
	v_lshl_add_u32 v192, v56, 4, v59
	s_add_u32 s16, s30, s16
	v_mov_b32_e32 v162, 0
	s_mov_b32 s42, 2
	v_cndmask_b32_e64 v201, v41, 1.0, vcc
	v_pk_fma_f32 v[80:81], v[16:17], s[4:5], v[40:41] op_sel_hi:[1,0,0]
	v_pk_fma_f32 v[78:79], v[14:15], s[4:5], v[40:41] op_sel_hi:[1,0,0]
	v_pk_fma_f32 v[76:77], v[12:13], s[4:5], v[40:41] op_sel_hi:[1,0,0]
	v_pk_fma_f32 v[74:75], v[10:11], s[4:5], v[40:41] op_sel_hi:[1,0,0]
	v_pk_fma_f32 v[72:73], v[8:9], s[4:5], v[40:41] op_sel_hi:[1,0,0]
	v_pk_fma_f32 v[70:71], v[6:7], s[4:5], v[40:41] op_sel_hi:[1,0,0]
	v_pk_fma_f32 v[68:69], v[4:5], s[4:5], v[40:41] op_sel_hi:[1,0,0]
	v_cmp_gt_u32_e64 s[2:3], 32, v183
	v_lshl_add_u32 v193, v38, 2, s24
	v_lshl_add_u32 v191, v58, 2, s24
	v_add_u32_e32 v190, 0x4000, v195
	v_add_u32_e32 v189, 0x4000, v196
	v_add_u32_e32 v188, 0x4000, v194
	v_add_u32_e32 v187, 0x4000, v192
	v_lshl_add_u64 v[166:167], s[22:23], 0, v[36:37]
	s_addc_u32 s17, s31, s17
	s_lshl_b32 s21, s41, 7
	v_lshl_add_u64 v[170:171], v[34:35], 0, s[18:19]
	s_movk_i32 s22, 0xc0
	v_mov_b32_e32 v2, 0
	v_mov_b32_e32 v3, v162
	v_mov_b32_e32 v4, v162
	v_mov_b32_e32 v5, v162
	v_mov_b32_e32 v6, v162
	v_mov_b32_e32 v7, v162
	v_mov_b32_e32 v8, v162
	v_mov_b32_e32 v9, v162
	v_mov_b32_e32 v10, v162
	v_mov_b32_e32 v11, v162
	v_mov_b32_e32 v12, v162
	v_mov_b32_e32 v13, v162
	v_mov_b32_e32 v14, v162
	v_mov_b32_e32 v15, v162
	v_mov_b32_e32 v16, v162
	v_mov_b32_e32 v17, v162
	v_mov_b32_e32 v18, 0
	v_mov_b32_e32 v19, v162
	v_mov_b32_e32 v20, v162
	v_mov_b32_e32 v21, v162
	v_mov_b32_e32 v22, v162
	v_mov_b32_e32 v23, v162
	v_mov_b32_e32 v24, v162
	v_mov_b32_e32 v25, v162
	v_mov_b32_e32 v26, v162
	v_mov_b32_e32 v27, v162
	v_mov_b32_e32 v28, v162
	v_mov_b32_e32 v29, v162
	v_mov_b32_e32 v30, v162
	v_mov_b32_e32 v31, v162
	v_mov_b32_e32 v32, v162
	v_mov_b32_e32 v33, v162
	v_mov_b32_e32 v34, 0
	v_mov_b32_e32 v35, v162
	v_mov_b32_e32 v36, v162
	v_mov_b32_e32 v37, v162
	v_mov_b32_e32 v38, v162
	v_mov_b32_e32 v39, v162
	v_mov_b32_e32 v40, v162
	v_mov_b32_e32 v41, v162
	v_mov_b32_e32 v42, v162
	v_mov_b32_e32 v43, v162
	v_mov_b32_e32 v44, v162
	v_mov_b32_e32 v45, v162
	v_mov_b32_e32 v46, v162
	v_mov_b32_e32 v47, v162
	v_mov_b32_e32 v48, v162
	v_mov_b32_e32 v49, v162
	v_mov_b32_e32 v50, 0
	v_mov_b32_e32 v51, v162
	v_mov_b32_e32 v52, v162
	v_mov_b32_e32 v53, v162
	v_mov_b32_e32 v54, v162
	v_mov_b32_e32 v55, v162
	v_mov_b32_e32 v56, v162
	v_mov_b32_e32 v57, v162
	v_mov_b32_e32 v58, v162
	v_mov_b32_e32 v59, v162
	v_mov_b32_e32 v60, v162
	v_mov_b32_e32 v61, v162
	v_mov_b32_e32 v62, v162
	v_mov_b32_e32 v63, v162
	v_mov_b32_e32 v64, v162
	v_mov_b32_e32 v65, v162
	.p2align 6

.LBB0_574:
	s_or_b64 exec, exec, s[0:1]
	s_movk_i32 s0, 0x57f
	ds_write_b32 v4, v6
	v_add_u32_e32 v6, 0x200, v5
	v_cmp_lt_i32_e64 s[0:1], s0, v5
	v_add_u32_e32 v4, 0x800, v4
	s_or_b64 s[10:11], s[0:1], s[10:11]
	v_mov_b32_e32 v5, v6
	s_andn2_b64 exec, exec, s[10:11]
	s_cbranch_execz .LBB0_577
	.p2align 6

.LBB0_584:
	s_waitcnt vmcnt(1)
	s_barrier
	s_addk_i32 s93, 0x80
	s_add_i32 s97, s83, 5
	s_cmp_ge_u32 s97, s78
	s_cbranch_scc1 .LBB0_736
	.p2align 6

.LBB0_885:
	s_waitcnt lgkmcnt(0)
	s_barrier
	s_setprio 1
	s_waitcnt lgkmcnt(0)
	v_mfma_f32_16x16x128_f8f6f4 v[126:129], v[26:33], v[58:65], v[126:129]
	v_mfma_f32_16x16x128_f8f6f4 v[122:125], v[18:25], v[58:65], v[122:125]
	v_mfma_f32_16x16x128_f8f6f4 v[110:113], v[26:33], v[50:57], v[110:113]
	v_mfma_f32_16x16x128_f8f6f4 v[106:109], v[18:25], v[50:57], v[106:109]
	v_mfma_f32_16x16x128_f8f6f4 v[94:97], v[26:33], v[42:49], v[94:97]
	v_mfma_f32_16x16x128_f8f6f4 v[90:93], v[18:25], v[42:49], v[90:93]
	v_mfma_f32_16x16x128_f8f6f4 v[78:81], v[26:33], v[34:41], v[78:81]
	v_mfma_f32_16x16x128_f8f6f4 v[74:77], v[18:25], v[34:41], v[74:77]
	s_setprio 0
	s_setprio 1
	v_mfma_f32_16x16x128_f8f6f4 v[118:121], v[10:17], v[58:65], v[118:121]
	v_mfma_f32_16x16x128_f8f6f4 v[114:117], v[2:9], v[58:65], v[114:117]
	v_mfma_f32_16x16x128_f8f6f4 v[102:105], v[10:17], v[50:57], v[102:105]
	v_mfma_f32_16x16x128_f8f6f4 v[98:101], v[2:9], v[50:57], v[98:101]
	v_mfma_f32_16x16x128_f8f6f4 v[86:89], v[10:17], v[42:49], v[86:89]
	v_mfma_f32_16x16x128_f8f6f4 v[82:85], v[2:9], v[42:49], v[82:85]
	v_mfma_f32_16x16x128_f8f6f4 v[70:73], v[10:17], v[34:41], v[70:73]
	v_mfma_f32_16x16x128_f8f6f4 v[66:69], v[2:9], v[34:41], v[66:69]
	s_setprio 0
	s_barrier
	v_add_u32_e32 v14, s48, v222
	v_add_u32_e32 v30, s53, v222
	ds_read_b128 v[2:5], v14
	ds_read_b128 v[6:9], v14 offset:1024
	ds_read_b128 v[10:13], v14 offset:2048
	ds_read_b128 v[14:17], v14 offset:3072
	ds_read_b128 v[18:21], v30
	ds_read_b128 v[22:25], v30 offset:1024
	ds_read_b128 v[26:29], v30 offset:2048
	ds_read_b128 v[30:33], v30 offset:3072
	s_add_u32 s28, s28, 0x530000
	s_addc_u32 s29, s29, 0
	s_mov_b32 m0, s42
	v_lshl_add_u64 v[228:229], s[28:29], 0, v[194:195]
	ds_read_b128 v[34:37], v226 offset:32768
	ds_read_b128 v[38:41], v226 offset:33792
	ds_read_b128 v[42:45], v226 offset:34816
	ds_read_b128 v[46:49], v226 offset:35840
	ds_read_b128 v[50:53], v226 offset:36864
	ds_read_b128 v[54:57], v226 offset:37888
	ds_read_b128 v[58:61], v226 offset:38912
	ds_read_b128 v[62:65], v226 offset:39936
	global_load_lds_dwordx4 v[228:229], off
	v_lshl_add_u64 v[228:229], s[28:29], 0, v[198:199]
	s_mov_b32 m0, s43
	s_nop 0
	global_load_lds_dwordx4 v[228:229], off
	s_waitcnt vmcnt(8)
	s_waitcnt lgkmcnt(0)
	s_barrier
	s_setprio 1
	s_waitcnt lgkmcnt(0)
	v_mfma_f32_16x16x128_f8f6f4 v[190:193], v[2:9], v[34:41], v[190:193]
	v_mfma_f32_16x16x128_f8f6f4 v[186:189], v[10:17], v[34:41], v[186:189]
	v_mfma_f32_16x16x128_f8f6f4 v[174:177], v[2:9], v[42:49], v[174:177]
	v_mfma_f32_16x16x128_f8f6f4 v[170:173], v[10:17], v[42:49], v[170:173]
	v_mfma_f32_16x16x128_f8f6f4 v[158:161], v[2:9], v[50:57], v[158:161]
	v_mfma_f32_16x16x128_f8f6f4 v[154:157], v[10:17], v[50:57], v[154:157]
	v_mfma_f32_16x16x128_f8f6f4 v[142:145], v[2:9], v[58:65], v[142:145]
	v_mfma_f32_16x16x128_f8f6f4 v[138:141], v[10:17], v[58:65], v[138:141]
	s_setprio 0
	s_setprio 1
	v_mfma_f32_16x16x128_f8f6f4 v[182:185], v[18:25], v[34:41], v[182:185]
	v_mfma_f32_16x16x128_f8f6f4 v[178:181], v[26:33], v[34:41], v[178:181]
	v_mfma_f32_16x16x128_f8f6f4 v[166:169], v[18:25], v[42:49], v[166:169]
	v_mfma_f32_16x16x128_f8f6f4 v[162:165], v[26:33], v[42:49], v[162:165]
	v_mfma_f32_16x16x128_f8f6f4 v[150:153], v[18:25], v[50:57], v[150:153]
	v_mfma_f32_16x16x128_f8f6f4 v[146:149], v[26:33], v[50:57], v[146:149]
	v_mfma_f32_16x16x128_f8f6f4 v[134:137], v[18:25], v[58:65], v[134:137]
	v_mfma_f32_16x16x128_f8f6f4 v[130:133], v[26:33], v[58:65], v[130:133]
	s_setprio 0
	s_barrier
	s_mov_b32 m0, s49
	v_lshl_add_u64 v[214:215], v[214:215], 0, s[14:15]
	s_add_u32 s26, s26, 0x40080
	ds_read_b128 v[34:37], v226 offset:49152
	ds_read_b128 v[38:41], v226 offset:50176
	ds_read_b128 v[42:45], v226 offset:51200
	ds_read_b128 v[46:49], v226 offset:52224
	ds_read_b128 v[50:53], v226 offset:53248
	ds_read_b128 v[54:57], v226 offset:54272
	ds_read_b128 v[58:61], v226 offset:55296
	ds_read_b128 v[62:65], v226 offset:56320
	global_load_lds_dwordx4 v[214:215], off
	v_lshl_add_u64 v[214:215], v[216:217], 0, s[14:15]
	s_mov_b32 m0, s50
	s_addc_u32 s27, s27, 0
	global_load_lds_dwordx4 v[214:215], off
	v_lshl_add_u64 v[214:215], s[26:27], 0, v[196:197]
	s_mov_b32 m0, s54
	s_nop 0
	global_load_lds_dwordx4 v[214:215], off
	v_lshl_add_u64 v[214:215], s[26:27], 0, v[200:201]
	s_mov_b32 m0, s55
	s_nop 0
	global_load_lds_dwordx4 v[214:215], off
	v_lshl_add_u64 v[214:215], v[218:219], 0, s[16:17]
	s_mov_b32 m0, s51
	s_nop 0
	global_load_lds_dwordx4 v[214:215], off
	v_lshl_add_u64 v[214:215], v[220:221], 0, s[16:17]
	s_mov_b32 m0, s52
	s_nop 0
	global_load_lds_dwordx4 v[214:215], off
	s_waitcnt vmcnt(8)
	s_waitcnt lgkmcnt(0)
	s_barrier
	s_setprio 1
	s_waitcnt lgkmcnt(0)
	v_mfma_f32_16x16x128_f8f6f4 v[126:129], v[2:9], v[34:41], v[126:129]
	v_mfma_f32_16x16x128_f8f6f4 v[122:125], v[10:17], v[34:41], v[122:125]
	v_mfma_f32_16x16x128_f8f6f4 v[110:113], v[2:9], v[42:49], v[110:113]
	v_mfma_f32_16x16x128_f8f6f4 v[106:109], v[10:17], v[42:49], v[106:109]
	v_mfma_f32_16x16x128_f8f6f4 v[94:97], v[2:9], v[50:57], v[94:97]
	v_mfma_f32_16x16x128_f8f6f4 v[90:93], v[10:17], v[50:57], v[90:93]
	v_mfma_f32_16x16x128_f8f6f4 v[78:81], v[2:9], v[58:65], v[78:81]
	v_mfma_f32_16x16x128_f8f6f4 v[74:77], v[10:17], v[58:65], v[74:77]
	s_setprio 0
	s_setprio 1
	v_mfma_f32_16x16x128_f8f6f4 v[118:121], v[18:25], v[34:41], v[118:121]
	v_mfma_f32_16x16x128_f8f6f4 v[114:117], v[26:33], v[34:41], v[114:117]
	v_mfma_f32_16x16x128_f8f6f4 v[102:105], v[18:25], v[42:49], v[102:105]
	v_mfma_f32_16x16x128_f8f6f4 v[98:101], v[26:33], v[42:49], v[98:101]
	v_mfma_f32_16x16x128_f8f6f4 v[86:89], v[18:25], v[50:57], v[86:89]
	v_mfma_f32_16x16x128_f8f6f4 v[82:85], v[26:33], v[50:57], v[82:85]
	v_mfma_f32_16x16x128_f8f6f4 v[70:73], v[18:25], v[58:65], v[70:73]
	v_mfma_f32_16x16x128_f8f6f4 v[66:69], v[26:33], v[58:65], v[66:69]
	s_setprio 0
	s_barrier
	s_add_i32 s70, s70, 2
	s_add_u32 s6, s6, 0x200
	s_addc_u32 s7, s7, 0
	s_add_u32 s68, s68, 0x100
	s_addc_u32 s69, s69, 0
	s_cmp_gt_u32 s70, 13
	s_cbranch_scc1 .LBB0_893
	.p2align 6

.LBB0_1062:
	s_waitcnt lgkmcnt(0)
	s_barrier
	s_setprio 1
	s_waitcnt lgkmcnt(0)
	v_mfma_f32_16x16x128_f8f6f4 v[126:129], v[26:33], v[58:65], v[126:129]
	v_mfma_f32_16x16x128_f8f6f4 v[122:125], v[18:25], v[58:65], v[122:125]
	v_mfma_f32_16x16x128_f8f6f4 v[114:117], v[26:33], v[50:57], v[114:117]
	v_mfma_f32_16x16x128_f8f6f4 v[106:109], v[18:25], v[50:57], v[106:109]
	v_mfma_f32_16x16x128_f8f6f4 v[98:101], v[26:33], v[42:49], v[98:101]
	v_mfma_f32_16x16x128_f8f6f4 v[90:93], v[18:25], v[42:49], v[90:93]
	v_mfma_f32_16x16x128_f8f6f4 v[82:85], v[26:33], v[34:41], v[82:85]
	v_mfma_f32_16x16x128_f8f6f4 v[74:77], v[18:25], v[34:41], v[74:77]
	s_setprio 0
	s_setprio 1
	v_mfma_f32_16x16x128_f8f6f4 v[118:121], v[10:17], v[58:65], v[118:121]
	v_mfma_f32_16x16x128_f8f6f4 v[110:113], v[2:9], v[58:65], v[110:113]
	v_mfma_f32_16x16x128_f8f6f4 v[102:105], v[10:17], v[50:57], v[102:105]
	v_mfma_f32_16x16x128_f8f6f4 v[94:97], v[2:9], v[50:57], v[94:97]
	v_mfma_f32_16x16x128_f8f6f4 v[86:89], v[10:17], v[42:49], v[86:89]
	v_mfma_f32_16x16x128_f8f6f4 v[78:81], v[2:9], v[42:49], v[78:81]
	v_mfma_f32_16x16x128_f8f6f4 v[70:73], v[10:17], v[34:41], v[70:73]
	v_mfma_f32_16x16x128_f8f6f4 v[66:69], v[2:9], v[34:41], v[66:69]
	s_setprio 0
	s_barrier
	v_add_u32_e32 v14, s58, v222
	v_add_u32_e32 v30, s63, v222
	ds_read_b128 v[2:5], v14
	ds_read_b128 v[6:9], v14 offset:1024
	ds_read_b128 v[10:13], v14 offset:2048
	ds_read_b128 v[14:17], v14 offset:3072
	ds_read_b128 v[18:21], v30
	ds_read_b128 v[22:25], v30 offset:1024
	ds_read_b128 v[26:29], v30 offset:2048
	ds_read_b128 v[30:33], v30 offset:3072
	s_add_u32 s40, s40, 0x40000
	s_addc_u32 s41, s41, 0
	s_mov_b32 m0, s56
	v_lshl_add_u64 v[228:229], s[40:41], 0, v[200:201]
	ds_read_b128 v[34:37], v226 offset:32768
	ds_read_b128 v[38:41], v226 offset:33792
	ds_read_b128 v[42:45], v226 offset:34816
	ds_read_b128 v[46:49], v226 offset:35840
	ds_read_b128 v[50:53], v226 offset:36864
	ds_read_b128 v[54:57], v226 offset:37888
	ds_read_b128 v[58:61], v226 offset:38912
	ds_read_b128 v[62:65], v226 offset:39936
	global_load_lds_dwordx4 v[228:229], off
	v_lshl_add_u64 v[228:229], s[40:41], 0, v[196:197]
	s_mov_b32 m0, s57
	s_nop 0
	global_load_lds_dwordx4 v[228:229], off
	s_waitcnt vmcnt(8)
	s_waitcnt lgkmcnt(0)
	s_barrier
	s_setprio 1
	s_waitcnt lgkmcnt(0)
	v_mfma_f32_16x16x128_f8f6f4 v[190:193], v[2:9], v[34:41], v[190:193]
	v_mfma_f32_16x16x128_f8f6f4 v[186:189], v[10:17], v[34:41], v[186:189]
	v_mfma_f32_16x16x128_f8f6f4 v[178:181], v[2:9], v[42:49], v[178:181]
	v_mfma_f32_16x16x128_f8f6f4 v[170:173], v[10:17], v[42:49], v[170:173]
	v_mfma_f32_16x16x128_f8f6f4 v[162:165], v[2:9], v[50:57], v[162:165]
	v_mfma_f32_16x16x128_f8f6f4 v[154:157], v[10:17], v[50:57], v[154:157]
	v_mfma_f32_16x16x128_f8f6f4 v[146:149], v[2:9], v[58:65], v[146:149]
	v_mfma_f32_16x16x128_f8f6f4 v[138:141], v[10:17], v[58:65], v[138:141]
	s_setprio 0
	s_setprio 1
	v_mfma_f32_16x16x128_f8f6f4 v[182:185], v[18:25], v[34:41], v[182:185]
	v_mfma_f32_16x16x128_f8f6f4 v[174:177], v[26:33], v[34:41], v[174:177]
	v_mfma_f32_16x16x128_f8f6f4 v[166:169], v[18:25], v[42:49], v[166:169]
	v_mfma_f32_16x16x128_f8f6f4 v[158:161], v[26:33], v[42:49], v[158:161]
	v_mfma_f32_16x16x128_f8f6f4 v[150:153], v[18:25], v[50:57], v[150:153]
	v_mfma_f32_16x16x128_f8f6f4 v[142:145], v[26:33], v[50:57], v[142:145]
	v_mfma_f32_16x16x128_f8f6f4 v[134:137], v[18:25], v[58:65], v[134:137]
	v_mfma_f32_16x16x128_f8f6f4 v[130:133], v[26:33], v[58:65], v[130:133]
	s_setprio 0
	s_barrier
	s_mov_b32 m0, s59
	v_lshl_add_u64 v[214:215], v[214:215], 0, s[6:7]
	s_add_u32 s38, s38, 0x40080
	ds_read_b128 v[34:37], v226 offset:49152
	ds_read_b128 v[38:41], v226 offset:50176
	ds_read_b128 v[42:45], v226 offset:51200
	ds_read_b128 v[46:49], v226 offset:52224
	ds_read_b128 v[50:53], v226 offset:53248
	ds_read_b128 v[54:57], v226 offset:54272
	ds_read_b128 v[58:61], v226 offset:55296
	ds_read_b128 v[62:65], v226 offset:56320
	global_load_lds_dwordx4 v[214:215], off
	v_lshl_add_u64 v[214:215], v[216:217], 0, s[6:7]
	s_mov_b32 m0, s60
	s_addc_u32 s39, s39, 0
	global_load_lds_dwordx4 v[214:215], off
	v_lshl_add_u64 v[214:215], s[38:39], 0, v[198:199]
	s_mov_b32 m0, s64
	s_nop 0
	global_load_lds_dwordx4 v[214:215], off
	v_lshl_add_u64 v[214:215], s[38:39], 0, v[194:195]
	s_mov_b32 m0, s65
	s_nop 0
	global_load_lds_dwordx4 v[214:215], off
	v_lshl_add_u64 v[214:215], v[218:219], 0, s[6:7]
	s_mov_b32 m0, s61
	s_nop 0
	global_load_lds_dwordx4 v[214:215], off
	v_lshl_add_u64 v[214:215], v[220:221], 0, s[6:7]
	s_mov_b32 m0, s62
	s_nop 0
	global_load_lds_dwordx4 v[214:215], off
	s_waitcnt vmcnt(8)
	s_waitcnt lgkmcnt(0)
	s_barrier
	s_setprio 1
	s_waitcnt lgkmcnt(0)
	v_mfma_f32_16x16x128_f8f6f4 v[126:129], v[2:9], v[34:41], v[126:129]
	v_mfma_f32_16x16x128_f8f6f4 v[122:125], v[10:17], v[34:41], v[122:125]
	v_mfma_f32_16x16x128_f8f6f4 v[114:117], v[2:9], v[42:49], v[114:117]
	v_mfma_f32_16x16x128_f8f6f4 v[106:109], v[10:17], v[42:49], v[106:109]
	v_mfma_f32_16x16x128_f8f6f4 v[98:101], v[2:9], v[50:57], v[98:101]
	v_mfma_f32_16x16x128_f8f6f4 v[90:93], v[10:17], v[50:57], v[90:93]
	v_mfma_f32_16x16x128_f8f6f4 v[82:85], v[2:9], v[58:65], v[82:85]
	v_mfma_f32_16x16x128_f8f6f4 v[74:77], v[10:17], v[58:65], v[74:77]
	s_setprio 0
	s_setprio 1
	v_mfma_f32_16x16x128_f8f6f4 v[118:121], v[18:25], v[34:41], v[118:121]
	v_mfma_f32_16x16x128_f8f6f4 v[110:113], v[26:33], v[34:41], v[110:113]
	v_mfma_f32_16x16x128_f8f6f4 v[102:105], v[18:25], v[42:49], v[102:105]
	v_mfma_f32_16x16x128_f8f6f4 v[94:97], v[26:33], v[42:49], v[94:97]
	v_mfma_f32_16x16x128_f8f6f4 v[86:89], v[18:25], v[50:57], v[86:89]
	v_mfma_f32_16x16x128_f8f6f4 v[78:81], v[26:33], v[50:57], v[78:81]
	v_mfma_f32_16x16x128_f8f6f4 v[70:73], v[18:25], v[58:65], v[70:73]
	v_mfma_f32_16x16x128_f8f6f4 v[66:69], v[26:33], v[58:65], v[66:69]
	s_setprio 0
	s_barrier
	s_add_i32 s77, s77, 2
	s_add_u32 s36, s36, 0x100
	s_addc_u32 s37, s37, 0
	s_cmp_gt_u32 s77, 13
	s_cbranch_scc1 .LBB0_1070
	.p2align 6

.LBB0_1225:
	s_waitcnt lgkmcnt(0)
	s_barrier
	s_setprio 1
	s_waitcnt lgkmcnt(0)
	v_mfma_f32_16x16x32_bf16 v[54:57], v[82:85], v[186:189], v[54:57]
	v_mfma_f32_16x16x32_bf16 v[46:49], v[90:93], v[186:189], v[46:49]
	v_mfma_f32_16x16x32_bf16 v[50:53], v[82:85], v[178:181], v[50:53]
	v_mfma_f32_16x16x32_bf16 v[38:41], v[90:93], v[178:181], v[38:41]
	v_mfma_f32_16x16x32_bf16 v[30:33], v[82:85], v[170:173], v[30:33]
	v_mfma_f32_16x16x32_bf16 v[22:25], v[90:93], v[170:173], v[22:25]
	v_mfma_f32_16x16x32_bf16 v[14:17], v[82:85], v[162:165], v[14:17]
	v_mfma_f32_16x16x32_bf16 v[10:13], v[90:93], v[162:165], v[10:13]
	v_mfma_f32_16x16x32_bf16 v[54:57], v[86:89], v[190:193], v[54:57]
	v_mfma_f32_16x16x32_bf16 v[46:49], v[94:97], v[190:193], v[46:49]
	v_mfma_f32_16x16x32_bf16 v[50:53], v[86:89], v[182:185], v[50:53]
	v_mfma_f32_16x16x32_bf16 v[38:41], v[94:97], v[182:185], v[38:41]
	v_mfma_f32_16x16x32_bf16 v[30:33], v[86:89], v[174:177], v[30:33]
	v_mfma_f32_16x16x32_bf16 v[22:25], v[94:97], v[174:177], v[22:25]
	v_mfma_f32_16x16x32_bf16 v[14:17], v[86:89], v[166:169], v[14:17]
	v_mfma_f32_16x16x32_bf16 v[10:13], v[94:97], v[166:169], v[10:13]
	s_setprio 0
	s_setprio 1
	v_mfma_f32_16x16x32_bf16 v[62:65], v[66:69], v[186:189], v[62:65]
	v_mfma_f32_16x16x32_bf16 v[58:61], v[74:77], v[186:189], v[58:61]
	v_mfma_f32_16x16x32_bf16 v[42:45], v[66:69], v[178:181], v[42:45]
	v_mfma_f32_16x16x32_bf16 v[34:37], v[74:77], v[178:181], v[34:37]
	v_mfma_f32_16x16x32_bf16 v[26:29], v[66:69], v[170:173], v[26:29]
	v_mfma_f32_16x16x32_bf16 v[18:21], v[74:77], v[170:173], v[18:21]
	v_mfma_f32_16x16x32_bf16 v[6:9], v[66:69], v[162:165], v[6:9]
	v_mfma_f32_16x16x32_bf16 v[2:5], v[74:77], v[162:165], v[2:5]
	v_mfma_f32_16x16x32_bf16 v[62:65], v[70:73], v[190:193], v[62:65]
	v_mfma_f32_16x16x32_bf16 v[58:61], v[78:81], v[190:193], v[58:61]
	v_mfma_f32_16x16x32_bf16 v[42:45], v[70:73], v[182:185], v[42:45]
	v_mfma_f32_16x16x32_bf16 v[34:37], v[78:81], v[182:185], v[34:37]
	v_mfma_f32_16x16x32_bf16 v[26:29], v[70:73], v[174:177], v[26:29]
	v_mfma_f32_16x16x32_bf16 v[18:21], v[78:81], v[174:177], v[18:21]
	v_mfma_f32_16x16x32_bf16 v[6:9], v[70:73], v[166:169], v[6:9]
	v_mfma_f32_16x16x32_bf16 v[2:5], v[78:81], v[166:169], v[2:5]
	s_setprio 0
	s_barrier
	v_add_u32_e32 v78, s74, v1
	v_add_u32_e32 v94, s79, v1
	ds_read_b128 v[66:69], v78
	ds_read_b128 v[70:73], v78 offset:1024
	ds_read_b128 v[74:77], v78 offset:2048
	ds_read_b128 v[78:81], v78 offset:3072
	ds_read_b128 v[82:85], v94
	ds_read_b128 v[86:89], v94 offset:1024
	ds_read_b128 v[90:93], v94 offset:2048
	ds_read_b128 v[94:97], v94 offset:3072
	s_add_u32 s54, s54, 0x80000
	s_addc_u32 s55, s55, 0
	s_mov_b32 m0, s70
	v_lshl_add_u64 v[234:235], s[54:55], 0, v[194:195]
	ds_read_b128 v[162:165], v231 offset:32768
	ds_read_b128 v[166:169], v231 offset:33792
	ds_read_b128 v[170:173], v231 offset:34816
	ds_read_b128 v[174:177], v231 offset:35840
	ds_read_b128 v[178:181], v231 offset:36864
	ds_read_b128 v[182:185], v231 offset:37888
	ds_read_b128 v[186:189], v231 offset:38912
	ds_read_b128 v[190:193], v231 offset:39936
	global_load_lds_dwordx4 v[234:235], off
	v_lshl_add_u64 v[234:235], s[54:55], 0, v[198:199]
	s_mov_b32 m0, s71
	s_nop 0
	global_load_lds_dwordx4 v[234:235], off
	s_waitcnt vmcnt(8)
	s_waitcnt lgkmcnt(0)
	s_barrier
	s_setprio 1
	s_waitcnt lgkmcnt(0)
	v_mfma_f32_16x16x32_bf16 v[150:153], v[66:69], v[162:165], v[150:153]
	v_mfma_f32_16x16x32_bf16 v[142:145], v[74:77], v[162:165], v[142:145]
	v_mfma_f32_16x16x32_bf16 v[146:149], v[66:69], v[170:173], v[146:149]
	v_mfma_f32_16x16x32_bf16 v[134:137], v[74:77], v[170:173], v[134:137]
	v_mfma_f32_16x16x32_bf16 v[126:129], v[66:69], v[178:181], v[126:129]
	v_mfma_f32_16x16x32_bf16 v[118:121], v[74:77], v[178:181], v[118:121]
	v_mfma_f32_16x16x32_bf16 v[110:113], v[66:69], v[186:189], v[110:113]
	v_mfma_f32_16x16x32_bf16 v[106:109], v[74:77], v[186:189], v[106:109]
	v_mfma_f32_16x16x32_bf16 v[150:153], v[70:73], v[166:169], v[150:153]
	v_mfma_f32_16x16x32_bf16 v[142:145], v[78:81], v[166:169], v[142:145]
	v_mfma_f32_16x16x32_bf16 v[146:149], v[70:73], v[174:177], v[146:149]
	v_mfma_f32_16x16x32_bf16 v[134:137], v[78:81], v[174:177], v[134:137]
	v_mfma_f32_16x16x32_bf16 v[126:129], v[70:73], v[182:185], v[126:129]
	v_mfma_f32_16x16x32_bf16 v[118:121], v[78:81], v[182:185], v[118:121]
	v_mfma_f32_16x16x32_bf16 v[110:113], v[70:73], v[190:193], v[110:113]
	v_mfma_f32_16x16x32_bf16 v[106:109], v[78:81], v[190:193], v[106:109]
	s_setprio 0
	s_setprio 1
	v_mfma_f32_16x16x32_bf16 v[158:161], v[82:85], v[162:165], v[158:161]
	v_mfma_f32_16x16x32_bf16 v[154:157], v[90:93], v[162:165], v[154:157]
	v_mfma_f32_16x16x32_bf16 v[138:141], v[82:85], v[170:173], v[138:141]
	v_mfma_f32_16x16x32_bf16 v[130:133], v[90:93], v[170:173], v[130:133]
	v_mfma_f32_16x16x32_bf16 v[122:125], v[82:85], v[178:181], v[122:125]
	v_mfma_f32_16x16x32_bf16 v[114:117], v[90:93], v[178:181], v[114:117]
	v_mfma_f32_16x16x32_bf16 v[102:105], v[82:85], v[186:189], v[102:105]
	v_mfma_f32_16x16x32_bf16 v[98:101], v[90:93], v[186:189], v[98:101]
	v_mfma_f32_16x16x32_bf16 v[158:161], v[86:89], v[166:169], v[158:161]
	v_mfma_f32_16x16x32_bf16 v[154:157], v[94:97], v[166:169], v[154:157]
	v_mfma_f32_16x16x32_bf16 v[138:141], v[86:89], v[174:177], v[138:141]
	v_mfma_f32_16x16x32_bf16 v[130:133], v[94:97], v[174:177], v[130:133]
	v_mfma_f32_16x16x32_bf16 v[122:125], v[86:89], v[182:185], v[122:125]
	v_mfma_f32_16x16x32_bf16 v[114:117], v[94:97], v[182:185], v[114:117]
	v_mfma_f32_16x16x32_bf16 v[102:105], v[86:89], v[190:193], v[102:105]
	v_mfma_f32_16x16x32_bf16 v[98:101], v[94:97], v[190:193], v[98:101]
	s_setprio 0
	s_barrier
	s_mov_b32 m0, s75
	v_lshl_add_u64 v[220:221], v[220:221], 0, s[24:25]
	s_add_u32 s52, s52, 0x80080
	ds_read_b128 v[162:165], v231 offset:49152
	ds_read_b128 v[166:169], v231 offset:50176
	ds_read_b128 v[170:173], v231 offset:51200
	ds_read_b128 v[174:177], v231 offset:52224
	ds_read_b128 v[178:181], v231 offset:53248
	ds_read_b128 v[182:185], v231 offset:54272
	ds_read_b128 v[186:189], v231 offset:55296
	ds_read_b128 v[190:193], v231 offset:56320
	global_load_lds_dwordx4 v[220:221], off
	v_lshl_add_u64 v[220:221], v[222:223], 0, s[24:25]
	s_mov_b32 m0, s76
	s_addc_u32 s53, s53, 0
	global_load_lds_dwordx4 v[220:221], off
	v_lshl_add_u64 v[220:221], s[52:53], 0, v[196:197]
	s_mov_b32 m0, s80
	s_nop 0
	global_load_lds_dwordx4 v[220:221], off
	v_lshl_add_u64 v[220:221], s[52:53], 0, v[200:201]
	s_mov_b32 m0, s81
	s_nop 0
	global_load_lds_dwordx4 v[220:221], off
	v_lshl_add_u64 v[220:221], v[224:225], 0, s[24:25]
	s_mov_b32 m0, s77
	s_nop 0
	global_load_lds_dwordx4 v[220:221], off
	v_lshl_add_u64 v[220:221], v[226:227], 0, s[24:25]
	s_mov_b32 m0, s78
	s_nop 0
	global_load_lds_dwordx4 v[220:221], off
	s_waitcnt vmcnt(8)
	s_waitcnt lgkmcnt(0)
	s_barrier
	s_setprio 1
	s_waitcnt lgkmcnt(0)
	v_mfma_f32_16x16x32_bf16 v[54:57], v[66:69], v[162:165], v[54:57]
	v_mfma_f32_16x16x32_bf16 v[46:49], v[74:77], v[162:165], v[46:49]
	v_mfma_f32_16x16x32_bf16 v[50:53], v[66:69], v[170:173], v[50:53]
	v_mfma_f32_16x16x32_bf16 v[38:41], v[74:77], v[170:173], v[38:41]
	v_mfma_f32_16x16x32_bf16 v[30:33], v[66:69], v[178:181], v[30:33]
	v_mfma_f32_16x16x32_bf16 v[22:25], v[74:77], v[178:181], v[22:25]
	v_mfma_f32_16x16x32_bf16 v[14:17], v[66:69], v[186:189], v[14:17]
	v_mfma_f32_16x16x32_bf16 v[10:13], v[74:77], v[186:189], v[10:13]
	v_mfma_f32_16x16x32_bf16 v[54:57], v[70:73], v[166:169], v[54:57]
	v_mfma_f32_16x16x32_bf16 v[46:49], v[78:81], v[166:169], v[46:49]
	v_mfma_f32_16x16x32_bf16 v[50:53], v[70:73], v[174:177], v[50:53]
	v_mfma_f32_16x16x32_bf16 v[38:41], v[78:81], v[174:177], v[38:41]
	v_mfma_f32_16x16x32_bf16 v[30:33], v[70:73], v[182:185], v[30:33]
	v_mfma_f32_16x16x32_bf16 v[22:25], v[78:81], v[182:185], v[22:25]
	v_mfma_f32_16x16x32_bf16 v[14:17], v[70:73], v[190:193], v[14:17]
	v_mfma_f32_16x16x32_bf16 v[10:13], v[78:81], v[190:193], v[10:13]
	s_setprio 0
	s_setprio 1
	v_mfma_f32_16x16x32_bf16 v[62:65], v[82:85], v[162:165], v[62:65]
	v_mfma_f32_16x16x32_bf16 v[58:61], v[90:93], v[162:165], v[58:61]
	v_mfma_f32_16x16x32_bf16 v[42:45], v[82:85], v[170:173], v[42:45]
	v_mfma_f32_16x16x32_bf16 v[34:37], v[90:93], v[170:173], v[34:37]
	v_mfma_f32_16x16x32_bf16 v[26:29], v[82:85], v[178:181], v[26:29]
	v_mfma_f32_16x16x32_bf16 v[18:21], v[90:93], v[178:181], v[18:21]
	v_mfma_f32_16x16x32_bf16 v[6:9], v[82:85], v[186:189], v[6:9]
	v_mfma_f32_16x16x32_bf16 v[2:5], v[90:93], v[186:189], v[2:5]
	v_mfma_f32_16x16x32_bf16 v[62:65], v[86:89], v[166:169], v[62:65]
	v_mfma_f32_16x16x32_bf16 v[58:61], v[94:97], v[166:169], v[58:61]
	v_mfma_f32_16x16x32_bf16 v[42:45], v[86:89], v[174:177], v[42:45]
	v_mfma_f32_16x16x32_bf16 v[34:37], v[94:97], v[174:177], v[34:37]
	v_mfma_f32_16x16x32_bf16 v[26:29], v[86:89], v[182:185], v[26:29]
	v_mfma_f32_16x16x32_bf16 v[18:21], v[94:97], v[182:185], v[18:21]
	v_mfma_f32_16x16x32_bf16 v[6:9], v[86:89], v[190:193], v[6:9]
	v_mfma_f32_16x16x32_bf16 v[2:5], v[94:97], v[190:193], v[2:5]
	s_setprio 0
	s_barrier
	s_add_i32 s93, s93, 2
	s_add_u32 s50, s50, 0x100
	s_addc_u32 s51, s51, 0
	s_cmp_gt_u32 s93, 29
	s_cbranch_scc1 .LBB0_1233
	.p2align 6

.LBB0_1397:
	s_waitcnt lgkmcnt(0)
	s_barrier
	s_setprio 1
	s_waitcnt lgkmcnt(0)
	v_mfma_f32_16x16x32_bf16 v[62:65], v[146:149], v[186:189], v[62:65]
	v_mfma_f32_16x16x32_bf16 v[58:61], v[154:157], v[186:189], v[58:61]
	v_mfma_f32_16x16x32_bf16 v[54:57], v[146:149], v[178:181], v[54:57]
	v_mfma_f32_16x16x32_bf16 v[46:49], v[154:157], v[178:181], v[46:49]
	v_mfma_f32_16x16x32_bf16 v[38:41], v[146:149], v[170:173], v[38:41]
	v_mfma_f32_16x16x32_bf16 v[30:33], v[154:157], v[170:173], v[30:33]
	v_mfma_f32_16x16x32_bf16 v[22:25], v[146:149], v[162:165], v[22:25]
	v_mfma_f32_16x16x32_bf16 v[14:17], v[154:157], v[162:165], v[14:17]
	v_mfma_f32_16x16x32_bf16 v[62:65], v[150:153], v[190:193], v[62:65]
	v_mfma_f32_16x16x32_bf16 v[58:61], v[158:161], v[190:193], v[58:61]
	v_mfma_f32_16x16x32_bf16 v[54:57], v[150:153], v[182:185], v[54:57]
	v_mfma_f32_16x16x32_bf16 v[46:49], v[158:161], v[182:185], v[46:49]
	v_mfma_f32_16x16x32_bf16 v[38:41], v[150:153], v[174:177], v[38:41]
	v_mfma_f32_16x16x32_bf16 v[30:33], v[158:161], v[174:177], v[30:33]
	v_mfma_f32_16x16x32_bf16 v[22:25], v[150:153], v[166:169], v[22:25]
	v_mfma_f32_16x16x32_bf16 v[14:17], v[158:161], v[166:169], v[14:17]
	s_setprio 0
	s_setprio 1
	v_mfma_f32_16x16x32_bf16 v[50:53], v[130:133], v[186:189], v[50:53]
	v_mfma_f32_16x16x32_bf16 v[42:45], v[138:141], v[186:189], v[42:45]
	v_mfma_f32_16x16x32_bf16 v[34:37], v[130:133], v[178:181], v[34:37]
	v_mfma_f32_16x16x32_bf16 v[26:29], v[138:141], v[178:181], v[26:29]
	v_mfma_f32_16x16x32_bf16 v[18:21], v[130:133], v[170:173], v[18:21]
	v_mfma_f32_16x16x32_bf16 v[10:13], v[138:141], v[170:173], v[10:13]
	v_mfma_f32_16x16x32_bf16 v[6:9], v[130:133], v[162:165], v[6:9]
	v_mfma_f32_16x16x32_bf16 v[2:5], v[138:141], v[162:165], v[2:5]
	v_mfma_f32_16x16x32_bf16 v[50:53], v[134:137], v[190:193], v[50:53]
	v_mfma_f32_16x16x32_bf16 v[42:45], v[142:145], v[190:193], v[42:45]
	v_mfma_f32_16x16x32_bf16 v[34:37], v[134:137], v[182:185], v[34:37]
	v_mfma_f32_16x16x32_bf16 v[26:29], v[142:145], v[182:185], v[26:29]
	v_mfma_f32_16x16x32_bf16 v[18:21], v[134:137], v[174:177], v[18:21]
	v_mfma_f32_16x16x32_bf16 v[10:13], v[142:145], v[174:177], v[10:13]
	v_mfma_f32_16x16x32_bf16 v[6:9], v[134:137], v[166:169], v[6:9]
	v_mfma_f32_16x16x32_bf16 v[2:5], v[142:145], v[166:169], v[2:5]
	s_setprio 0
	s_barrier
	v_add_u32_e32 v142, s52, v222
	v_add_u32_e32 v158, s57, v222
	ds_read_b128 v[130:133], v142
	ds_read_b128 v[134:137], v142 offset:1024
	ds_read_b128 v[138:141], v142 offset:2048
	ds_read_b128 v[142:145], v142 offset:3072
	ds_read_b128 v[146:149], v158
	ds_read_b128 v[150:153], v158 offset:1024
	ds_read_b128 v[154:157], v158 offset:2048
	ds_read_b128 v[158:161], v158 offset:3072
	s_add_u32 s30, s30, 0x160000
	s_addc_u32 s31, s31, 0
	s_mov_b32 m0, s50
	v_lshl_add_u64 v[228:229], s[30:31], 0, v[200:201]
	ds_read_b128 v[162:165], v226 offset:32768
	ds_read_b128 v[166:169], v226 offset:33792
	ds_read_b128 v[170:173], v226 offset:34816
	ds_read_b128 v[174:177], v226 offset:35840
	ds_read_b128 v[178:181], v226 offset:36864
	ds_read_b128 v[182:185], v226 offset:37888
	ds_read_b128 v[186:189], v226 offset:38912
	ds_read_b128 v[190:193], v226 offset:39936
	global_load_lds_dwordx4 v[228:229], off
	v_lshl_add_u64 v[228:229], s[30:31], 0, v[196:197]
	s_mov_b32 m0, s51
	s_nop 0
	global_load_lds_dwordx4 v[228:229], off
	s_waitcnt vmcnt(8)
	s_waitcnt lgkmcnt(0)
	s_barrier
	s_setprio 1
	s_waitcnt lgkmcnt(0)
	v_mfma_f32_16x16x32_bf16 v[126:129], v[130:133], v[162:165], v[126:129]
	v_mfma_f32_16x16x32_bf16 v[122:125], v[138:141], v[162:165], v[122:125]
	v_mfma_f32_16x16x32_bf16 v[118:121], v[130:133], v[170:173], v[118:121]
	v_mfma_f32_16x16x32_bf16 v[110:113], v[138:141], v[170:173], v[110:113]
	v_mfma_f32_16x16x32_bf16 v[102:105], v[130:133], v[178:181], v[102:105]
	v_mfma_f32_16x16x32_bf16 v[94:97], v[138:141], v[178:181], v[94:97]
	v_mfma_f32_16x16x32_bf16 v[86:89], v[130:133], v[186:189], v[86:89]
	v_mfma_f32_16x16x32_bf16 v[78:81], v[138:141], v[186:189], v[78:81]
	v_mfma_f32_16x16x32_bf16 v[126:129], v[134:137], v[166:169], v[126:129]
	v_mfma_f32_16x16x32_bf16 v[122:125], v[142:145], v[166:169], v[122:125]
	v_mfma_f32_16x16x32_bf16 v[118:121], v[134:137], v[174:177], v[118:121]
	v_mfma_f32_16x16x32_bf16 v[110:113], v[142:145], v[174:177], v[110:113]
	v_mfma_f32_16x16x32_bf16 v[102:105], v[134:137], v[182:185], v[102:105]
	v_mfma_f32_16x16x32_bf16 v[94:97], v[142:145], v[182:185], v[94:97]
	v_mfma_f32_16x16x32_bf16 v[86:89], v[134:137], v[190:193], v[86:89]
	v_mfma_f32_16x16x32_bf16 v[78:81], v[142:145], v[190:193], v[78:81]
	s_setprio 0
	s_setprio 1
	v_mfma_f32_16x16x32_bf16 v[114:117], v[146:149], v[162:165], v[114:117]
	v_mfma_f32_16x16x32_bf16 v[106:109], v[154:157], v[162:165], v[106:109]
	v_mfma_f32_16x16x32_bf16 v[98:101], v[146:149], v[170:173], v[98:101]
	v_mfma_f32_16x16x32_bf16 v[90:93], v[154:157], v[170:173], v[90:93]
	v_mfma_f32_16x16x32_bf16 v[82:85], v[146:149], v[178:181], v[82:85]
	v_mfma_f32_16x16x32_bf16 v[74:77], v[154:157], v[178:181], v[74:77]
	v_mfma_f32_16x16x32_bf16 v[70:73], v[146:149], v[186:189], v[70:73]
	v_mfma_f32_16x16x32_bf16 v[66:69], v[154:157], v[186:189], v[66:69]
	v_mfma_f32_16x16x32_bf16 v[114:117], v[150:153], v[166:169], v[114:117]
	v_mfma_f32_16x16x32_bf16 v[106:109], v[158:161], v[166:169], v[106:109]
	v_mfma_f32_16x16x32_bf16 v[98:101], v[150:153], v[174:177], v[98:101]
	v_mfma_f32_16x16x32_bf16 v[90:93], v[158:161], v[174:177], v[90:93]
	v_mfma_f32_16x16x32_bf16 v[82:85], v[150:153], v[182:185], v[82:85]
	v_mfma_f32_16x16x32_bf16 v[74:77], v[158:161], v[182:185], v[74:77]
	v_mfma_f32_16x16x32_bf16 v[70:73], v[150:153], v[190:193], v[70:73]
	v_mfma_f32_16x16x32_bf16 v[66:69], v[158:161], v[190:193], v[66:69]
	s_setprio 0
	s_barrier
	s_mov_b32 m0, s53
	v_lshl_add_u64 v[214:215], v[214:215], 0, s[8:9]
	s_add_u32 s28, s28, 0x160080
	ds_read_b128 v[162:165], v226 offset:49152
	ds_read_b128 v[166:169], v226 offset:50176
	ds_read_b128 v[170:173], v226 offset:51200
	ds_read_b128 v[174:177], v226 offset:52224
	ds_read_b128 v[178:181], v226 offset:53248
	ds_read_b128 v[182:185], v226 offset:54272
	ds_read_b128 v[186:189], v226 offset:55296
	ds_read_b128 v[190:193], v226 offset:56320
	global_load_lds_dwordx4 v[214:215], off
	v_lshl_add_u64 v[214:215], v[216:217], 0, s[8:9]
	s_mov_b32 m0, s54
	s_addc_u32 s29, s29, 0
	global_load_lds_dwordx4 v[214:215], off
	v_lshl_add_u64 v[214:215], s[28:29], 0, v[198:199]
	s_mov_b32 m0, s58
	s_nop 0
	global_load_lds_dwordx4 v[214:215], off
	v_lshl_add_u64 v[214:215], s[28:29], 0, v[194:195]
	s_mov_b32 m0, s59
	s_nop 0
	global_load_lds_dwordx4 v[214:215], off
	v_lshl_add_u64 v[214:215], v[218:219], 0, s[8:9]
	s_mov_b32 m0, s55
	s_nop 0
	global_load_lds_dwordx4 v[214:215], off
	v_lshl_add_u64 v[214:215], v[220:221], 0, s[8:9]
	s_mov_b32 m0, s56
	s_nop 0
	global_load_lds_dwordx4 v[214:215], off
	s_waitcnt vmcnt(8)
	s_waitcnt lgkmcnt(0)
	s_barrier
	s_setprio 1
	s_waitcnt lgkmcnt(0)
	v_mfma_f32_16x16x32_bf16 v[62:65], v[130:133], v[162:165], v[62:65]
	v_mfma_f32_16x16x32_bf16 v[58:61], v[138:141], v[162:165], v[58:61]
	v_mfma_f32_16x16x32_bf16 v[54:57], v[130:133], v[170:173], v[54:57]
	v_mfma_f32_16x16x32_bf16 v[46:49], v[138:141], v[170:173], v[46:49]
	v_mfma_f32_16x16x32_bf16 v[38:41], v[130:133], v[178:181], v[38:41]
	v_mfma_f32_16x16x32_bf16 v[30:33], v[138:141], v[178:181], v[30:33]
	v_mfma_f32_16x16x32_bf16 v[22:25], v[130:133], v[186:189], v[22:25]
	v_mfma_f32_16x16x32_bf16 v[14:17], v[138:141], v[186:189], v[14:17]
	v_mfma_f32_16x16x32_bf16 v[62:65], v[134:137], v[166:169], v[62:65]
	v_mfma_f32_16x16x32_bf16 v[58:61], v[142:145], v[166:169], v[58:61]
	v_mfma_f32_16x16x32_bf16 v[54:57], v[134:137], v[174:177], v[54:57]
	v_mfma_f32_16x16x32_bf16 v[46:49], v[142:145], v[174:177], v[46:49]
	v_mfma_f32_16x16x32_bf16 v[38:41], v[134:137], v[182:185], v[38:41]
	v_mfma_f32_16x16x32_bf16 v[30:33], v[142:145], v[182:185], v[30:33]
	v_mfma_f32_16x16x32_bf16 v[22:25], v[134:137], v[190:193], v[22:25]
	v_mfma_f32_16x16x32_bf16 v[14:17], v[142:145], v[190:193], v[14:17]
	s_setprio 0
	s_setprio 1
	v_mfma_f32_16x16x32_bf16 v[50:53], v[146:149], v[162:165], v[50:53]
	v_mfma_f32_16x16x32_bf16 v[42:45], v[154:157], v[162:165], v[42:45]
	v_mfma_f32_16x16x32_bf16 v[34:37], v[146:149], v[170:173], v[34:37]
	v_mfma_f32_16x16x32_bf16 v[26:29], v[154:157], v[170:173], v[26:29]
	v_mfma_f32_16x16x32_bf16 v[18:21], v[146:149], v[178:181], v[18:21]
	v_mfma_f32_16x16x32_bf16 v[10:13], v[154:157], v[178:181], v[10:13]
	v_mfma_f32_16x16x32_bf16 v[6:9], v[146:149], v[186:189], v[6:9]
	v_mfma_f32_16x16x32_bf16 v[2:5], v[154:157], v[186:189], v[2:5]
	v_mfma_f32_16x16x32_bf16 v[50:53], v[150:153], v[166:169], v[50:53]
	v_mfma_f32_16x16x32_bf16 v[42:45], v[158:161], v[166:169], v[42:45]
	v_mfma_f32_16x16x32_bf16 v[34:37], v[150:153], v[174:177], v[34:37]
	v_mfma_f32_16x16x32_bf16 v[26:29], v[158:161], v[174:177], v[26:29]
	v_mfma_f32_16x16x32_bf16 v[18:21], v[150:153], v[182:185], v[18:21]
	v_mfma_f32_16x16x32_bf16 v[10:13], v[158:161], v[182:185], v[10:13]
	v_mfma_f32_16x16x32_bf16 v[6:9], v[150:153], v[190:193], v[6:9]
	v_mfma_f32_16x16x32_bf16 v[2:5], v[158:161], v[190:193], v[2:5]
	s_setprio 0
	s_barrier
	s_add_i32 s72, s72, 2
	s_add_u32 s26, s26, 0x100
	s_addc_u32 s27, s27, 0
	s_cmpk_gt_u32 s72, 0x55
	s_cbranch_scc1 .LBB0_1405
	.p2align 6

.LBB0_1848:
	s_waitcnt vmcnt(0)
	v_lshlrev_b32_e32 v58, 16, v46
	v_and_b32_e32 v46, 0xffff0000, v46
	v_mov_b32_e32 v146, v171
	v_cvt_pk_fp8_f32 v146, v58, v46
	v_lshlrev_b32_e32 v58, 16, v48
	v_and_b32_e32 v48, 0xffff0000, v48
	v_mov_b32_e32 v147, v171
	v_cvt_pk_fp8_f32 v147, v58, v48
	v_lshlrev_b32_e32 v46, 16, v47
	v_and_b32_e32 v47, 0xffff0000, v47
	v_cvt_pk_fp8_f32 v146, v46, v47 op_sel:[0,0,1]
	v_lshlrev_b32_e32 v46, 16, v49
	v_and_b32_e32 v47, 0xffff0000, v49
	v_cvt_pk_fp8_f32 v147, v46, v47 op_sel:[0,0,1]
	v_lshlrev_b32_e32 v46, 16, v42
	v_and_b32_e32 v42, 0xffff0000, v42
	v_mov_b32_e32 v148, v171
	v_cvt_pk_fp8_f32 v148, v46, v42
	v_lshlrev_b32_e32 v46, 16, v44
	v_and_b32_e32 v44, 0xffff0000, v44
	v_mov_b32_e32 v149, v171
	v_cvt_pk_fp8_f32 v149, v46, v44
	v_lshlrev_b32_e32 v42, 16, v43
	v_and_b32_e32 v43, 0xffff0000, v43
	v_cvt_pk_fp8_f32 v148, v42, v43 op_sel:[0,0,1]
	v_lshlrev_b32_e32 v42, 16, v45
	v_and_b32_e32 v43, 0xffff0000, v45
	v_cvt_pk_fp8_f32 v149, v42, v43 op_sel:[0,0,1]
	v_lshlrev_b32_e32 v42, 16, v38
	v_and_b32_e32 v38, 0xffff0000, v38
	v_mov_b32_e32 v150, v171
	v_cvt_pk_fp8_f32 v150, v42, v38
	v_lshlrev_b32_e32 v42, 16, v40
	v_and_b32_e32 v40, 0xffff0000, v40
	v_mov_b32_e32 v151, v171
	v_cvt_pk_fp8_f32 v151, v42, v40
	v_lshlrev_b32_e32 v38, 16, v39
	v_and_b32_e32 v39, 0xffff0000, v39
	v_cvt_pk_fp8_f32 v150, v38, v39 op_sel:[0,0,1]
	v_lshlrev_b32_e32 v38, 16, v41
	v_and_b32_e32 v39, 0xffff0000, v41
	v_cvt_pk_fp8_f32 v151, v38, v39 op_sel:[0,0,1]
	v_lshlrev_b32_e32 v38, 16, v34
	v_and_b32_e32 v34, 0xffff0000, v34
	v_mov_b32_e32 v152, v171
	v_cvt_pk_fp8_f32 v152, v38, v34
	v_lshlrev_b32_e32 v38, 16, v36
	v_and_b32_e32 v36, 0xffff0000, v36
	v_mov_b32_e32 v153, v171
	v_cvt_pk_fp8_f32 v153, v38, v36
	v_lshlrev_b32_e32 v34, 16, v35
	v_and_b32_e32 v35, 0xffff0000, v35
	v_cvt_pk_fp8_f32 v152, v34, v35 op_sel:[0,0,1]
	v_lshlrev_b32_e32 v34, 16, v37
	v_and_b32_e32 v35, 0xffff0000, v37
	v_cvt_pk_fp8_f32 v153, v34, v35 op_sel:[0,0,1]
	v_lshlrev_b32_e32 v34, 16, v30
	v_and_b32_e32 v30, 0xffff0000, v30
	v_mov_b32_e32 v154, v171
	v_cvt_pk_fp8_f32 v154, v34, v30
	v_lshlrev_b32_e32 v34, 16, v32
	v_and_b32_e32 v32, 0xffff0000, v32
	v_mov_b32_e32 v155, v171
	v_cvt_pk_fp8_f32 v155, v34, v32
	v_lshlrev_b32_e32 v30, 16, v31
	v_and_b32_e32 v31, 0xffff0000, v31
	v_cvt_pk_fp8_f32 v154, v30, v31 op_sel:[0,0,1]
	v_lshlrev_b32_e32 v30, 16, v33
	v_and_b32_e32 v31, 0xffff0000, v33
	v_cvt_pk_fp8_f32 v155, v30, v31 op_sel:[0,0,1]
	v_lshlrev_b32_e32 v30, 16, v26
	v_and_b32_e32 v26, 0xffff0000, v26
	v_mov_b32_e32 v156, v171
	v_cvt_pk_fp8_f32 v156, v30, v26
	v_lshlrev_b32_e32 v30, 16, v28
	v_and_b32_e32 v28, 0xffff0000, v28
	v_mov_b32_e32 v157, v171
	v_cvt_pk_fp8_f32 v157, v30, v28
	v_lshlrev_b32_e32 v26, 16, v27
	v_and_b32_e32 v27, 0xffff0000, v27
	v_cvt_pk_fp8_f32 v156, v26, v27 op_sel:[0,0,1]
	v_lshlrev_b32_e32 v26, 16, v29
	v_and_b32_e32 v27, 0xffff0000, v29
	v_cvt_pk_fp8_f32 v157, v26, v27 op_sel:[0,0,1]
	v_lshlrev_b32_e32 v26, 16, v22
	v_and_b32_e32 v22, 0xffff0000, v22
	v_mov_b32_e32 v158, v171
	v_cvt_pk_fp8_f32 v158, v26, v22
	v_lshlrev_b32_e32 v26, 16, v24
	v_and_b32_e32 v24, 0xffff0000, v24
	v_mov_b32_e32 v159, v171
	v_cvt_pk_fp8_f32 v159, v26, v24
	v_lshlrev_b32_e32 v22, 16, v23
	v_and_b32_e32 v23, 0xffff0000, v23
	v_cvt_pk_fp8_f32 v158, v22, v23 op_sel:[0,0,1]
	v_lshlrev_b32_e32 v22, 16, v25
	v_and_b32_e32 v23, 0xffff0000, v25
	v_cvt_pk_fp8_f32 v159, v22, v23 op_sel:[0,0,1]
	v_lshlrev_b32_e32 v22, 16, v18
	v_and_b32_e32 v18, 0xffff0000, v18
	v_mov_b32_e32 v160, v171
	v_cvt_pk_fp8_f32 v160, v22, v18
	v_lshlrev_b32_e32 v22, 16, v20
	v_and_b32_e32 v20, 0xffff0000, v20
	v_mov_b32_e32 v161, v171
	v_cvt_pk_fp8_f32 v161, v22, v20
	v_lshlrev_b32_e32 v18, 16, v19
	v_and_b32_e32 v19, 0xffff0000, v19
	v_cvt_pk_fp8_f32 v160, v18, v19 op_sel:[0,0,1]
	v_lshlrev_b32_e32 v18, 16, v21
	v_and_b32_e32 v19, 0xffff0000, v21
	v_cvt_pk_fp8_f32 v161, v18, v19 op_sel:[0,0,1]
	v_lshlrev_b32_e32 v18, 16, v14
	v_and_b32_e32 v14, 0xffff0000, v14
	v_mov_b32_e32 v162, v171
	v_cvt_pk_fp8_f32 v162, v18, v14
	v_lshlrev_b32_e32 v18, 16, v16
	v_and_b32_e32 v16, 0xffff0000, v16
	v_mov_b32_e32 v163, v171
	v_cvt_pk_fp8_f32 v163, v18, v16
	v_lshlrev_b32_e32 v14, 16, v15
	v_and_b32_e32 v15, 0xffff0000, v15
	v_cvt_pk_fp8_f32 v162, v14, v15 op_sel:[0,0,1]
	v_lshlrev_b32_e32 v14, 16, v17
	v_and_b32_e32 v15, 0xffff0000, v17
	v_cvt_pk_fp8_f32 v163, v14, v15 op_sel:[0,0,1]
	v_lshlrev_b32_e32 v14, 16, v10
	v_and_b32_e32 v10, 0xffff0000, v10
	v_mov_b32_e32 v164, v171
	v_cvt_pk_fp8_f32 v164, v14, v10
	v_lshlrev_b32_e32 v14, 16, v12
	v_and_b32_e32 v12, 0xffff0000, v12
	v_mov_b32_e32 v165, v171
	v_cvt_pk_fp8_f32 v165, v14, v12
	v_lshlrev_b32_e32 v10, 16, v11
	v_and_b32_e32 v11, 0xffff0000, v11
	v_cvt_pk_fp8_f32 v164, v10, v11 op_sel:[0,0,1]
	v_lshlrev_b32_e32 v10, 16, v13
	v_and_b32_e32 v11, 0xffff0000, v13
	v_cvt_pk_fp8_f32 v165, v10, v11 op_sel:[0,0,1]
	v_lshlrev_b32_e32 v10, 16, v6
	v_and_b32_e32 v6, 0xffff0000, v6
	v_mov_b32_e32 v166, v171
	v_cvt_pk_fp8_f32 v166, v10, v6
	v_lshlrev_b32_e32 v10, 16, v8
	v_and_b32_e32 v8, 0xffff0000, v8
	v_mov_b32_e32 v167, v171
	v_cvt_pk_fp8_f32 v167, v10, v8
	v_lshlrev_b32_e32 v6, 16, v7
	v_and_b32_e32 v7, 0xffff0000, v7
	v_cvt_pk_fp8_f32 v166, v6, v7 op_sel:[0,0,1]
	v_lshlrev_b32_e32 v6, 16, v9
	v_and_b32_e32 v7, 0xffff0000, v9
	v_cvt_pk_fp8_f32 v167, v6, v7 op_sel:[0,0,1]
	v_lshlrev_b32_e32 v6, 16, v2
	v_and_b32_e32 v2, 0xffff0000, v2
	v_mov_b32_e32 v168, v171
	v_cvt_pk_fp8_f32 v168, v6, v2
	v_lshlrev_b32_e32 v6, 16, v4
	v_and_b32_e32 v4, 0xffff0000, v4
	v_mov_b32_e32 v169, v171
	v_cvt_pk_fp8_f32 v169, v6, v4
	v_lshlrev_b32_e32 v2, 16, v3
	v_and_b32_e32 v3, 0xffff0000, v3
	v_cvt_pk_fp8_f32 v168, v2, v3 op_sel:[0,0,1]
	v_lshlrev_b32_e32 v2, 16, v5
	v_and_b32_e32 v3, 0xffff0000, v5
	v_cvt_pk_fp8_f32 v169, v2, v3 op_sel:[0,0,1]
	v_lshrrev_b32_e32 v2, 1, v55
	v_and_b32_e32 v3, 8, v55
	v_and_or_b32 v2, v2, 3, v3
	v_bfe_u32 v58, v55, 5, 1
	v_bfe_u32 v59, v55, 1, 3
	v_lshlrev_b32_e32 v2, 7, v2
	v_lshlrev_b32_e32 v3, 3, v55
	v_and_b32_e32 v60, 1, v57
	v_lshl_or_b32 v2, v58, 9, v2
	v_and_b32_e32 v3, 8, v3
	v_bitop3_b32 v10, v57, v59, 1 bitop3:0x6c
	v_lshlrev_b32_e32 v42, 3, v52
	v_or_b32_e32 v57, 32, v52
	v_add3_u32 v61, v3, s67, v2
	s_waitcnt lgkmcnt(0)
	v_bitop3_b32 v11, v42, v56, s45 bitop3:0x6c
	v_lshl_add_u32 v43, v52, 7, s67
	v_or_b32_e32 v2, 16, v56
	v_lshl_add_u32 v44, v57, 7, s67
	s_barrier
	v_add_u32_e32 v209, v43, v11
	v_bitop3_b32 v12, v42, v2, s45 bitop3:0x6c
	v_add_u32_e32 v211, v44, v11
	v_add_u32_e32 v210, v43, v12
	ds_read_b128 v[2:5], v209 offset:32768
	ds_read_b128 v[6:9], v210 offset:32768
	v_add_u32_e32 v212, v44, v12
	ds_read_b128 v[34:37], v211 offset:32768
	ds_read_b128 v[38:41], v212 offset:32768
	v_lshl_add_u32 v206, v10, 4, v61
	v_bitop3_b32 v10, v60, v59, 2 bitop3:0x36
	v_lshl_add_u32 v205, v10, 4, v61
	s_waitcnt lgkmcnt(0)
	v_mfma_f32_32x32x64_f8f6f4 v[18:33], v[2:9], v[146:153], 0
	v_mfma_f32_32x32x64_f8f6f4 v[2:17], v[34:41], v[146:153], 0
	v_or_b32_e32 v34, 64, v56
	v_bitop3_b32 v45, v42, v34, s45 bitop3:0x6c
	v_or_b32_e32 v34, 0x50, v56
	v_add_u32_e32 v213, v43, v45
	v_bitop3_b32 v42, v42, v34, s45 bitop3:0x6c
	v_add_u32_e32 v214, v43, v42
	ds_read_b128 v[34:37], v213 offset:32768
	ds_read_b128 v[38:41], v214 offset:32768
	v_add_u32_e32 v207, v44, v45
	v_add_u32_e32 v208, v44, v42
	ds_read_b128 v[42:45], v207 offset:32768
	ds_read_b128 v[46:49], v208 offset:32768
	v_bitop3_b32 v56, v60, v59, 4 bitop3:0x36
	s_waitcnt lgkmcnt(2)
	v_mfma_f32_32x32x64_f8f6f4 v[18:33], v[34:41], v[154:161], v[18:33]
	v_lshlrev_b32_e32 v34, 1, v58
	v_lshrrev_b32_e32 v35, 2, v55
	v_and_b32_e32 v195, 63, v55
	v_lshl_add_u32 v203, v56, 4, v61
	v_bitop3_b32 v56, v60, v59, 6 bitop3:0x36
	v_lshlrev_b32_e32 v59, 6, v52
	v_bfe_u32 v36, v55, 2, 2
	v_bitop3_b32 v35, v34, v35, 3 bitop3:0x78
	v_lshlrev_b32_e32 v55, 6, v57
	s_waitcnt lgkmcnt(0)
	v_mfma_f32_32x32x64_f8f6f4 v[2:17], v[42:49], v[154:161], v[2:17]
	v_lshlrev_b32_e32 v215, 4, v35
	v_add_u32_e32 v35, s42, v59
	v_bitop3_b32 v34, v34, v36, 1 bitop3:0x36
	v_add_u32_e32 v42, s42, v55
	v_add_u32_e32 v216, v35, v215
	v_lshlrev_b32_e32 v217, 4, v34
	v_add_u32_e32 v219, v42, v215
	v_add_u32_e32 v218, v35, v217
	ds_read_b128 v[34:37], v216
	ds_read_b128 v[38:41], v218
	v_add_u32_e32 v220, v42, v217
	ds_read_b128 v[42:45], v219
	ds_read_b128 v[46:49], v220
	s_waitcnt lgkmcnt(2)
	v_mfma_f32_32x32x64_f8f6f4 v[18:33], v[34:41], v[162:169], v[18:33]
	s_waitcnt lgkmcnt(0)
	v_mfma_f32_32x32x64_f8f6f4 v[2:17], v[42:49], v[162:169], v[2:17]
	s_nop 0
	s_nop 15
	s_nop 7
	s_lshr_b32 s2, s58, 3
	v_max_f32_e32 v34, v19, v19
	v_max_f32_e32 v35, v18, v18
	v_max_f32_e32 v34, v35, v34
	v_max3_f32 v34, v34, v20, v21
	v_max3_f32 v34, v34, v22, v23
	v_max3_f32 v34, v34, v24, v25
	v_max3_f32 v34, v34, v26, v27
	v_max3_f32 v34, v34, v28, v29
	v_max3_f32 v34, v34, v30, v31
	v_max3_f32 v34, v34, v32, v33
	v_max3_f32 v34, v34, v2, v3
	v_max3_f32 v34, v34, v4, v5
	v_max3_f32 v34, v34, v6, v7
	v_max3_f32 v34, v34, v8, v9
	v_max3_f32 v34, v34, v10, v11
	v_max3_f32 v34, v34, v12, v13
	v_max3_f32 v34, v34, v14, v15
	v_max3_f32 v34, v34, v16, v17
	v_mov_b32_e32 v35, v34
	s_nop 1
	v_permlane32_swap_b32_e32 v34, v35
	v_max_f32_e32 v35, v35, v35
	v_max_f32_e32 v34, v34, v34
	s_and_b32 s3, s59, 0x3fffffc0
	v_max_f32_e32 v34, v34, v35
	s_lshl_b32 s3, s3, 2
	s_and_b32 s2, s2, 15
	v_add_f32_e32 v35, 0x7149f2ca, v34
	s_add_i32 s36, s71, s3
	s_lshl_b32 s58, s2, 7
	v_cmp_ge_f32_e32 vcc, s46, v35
	s_cmp_eq_u64 vcc, exec
	v_max_f32_e32 v34, 0xf149f2ca, v34
	s_cselect_b64 vcc, -1, 0
	v_cndmask_b32_e32 v228, v34, v194, vcc
	v_sub_f32_e32 v36, 0xf149f2ca, v34
	v_fma_f32 v34, v228, s47, 4.0
	v_mov_b32_e32 v35, v34
	s_add_u32 s2, s54, s34
	v_fmac_f32_e32 v35, 0x3dd53b94, v33
	s_addc_u32 s3, s55, s35
	s_add_i32 s37, s67, s57
	v_pk_fma_f32 v[66:67], v[2:3], s[4:5], v[34:35] op_sel_hi:[1,0,0]
	v_lshl_add_u64 v[2:3], s[2:3], 0, v[174:175]
	s_add_i32 s57, s37, 0x4000
	v_lshl_add_u64 v[2:3], v[2:3], 0, s[6:7]
	s_mov_b32 m0, s57
	v_mul_f32_e32 v36, 0x3dd53b94, v36
	global_load_lds_dwordx4 v[2:3], off
	v_exp_f32_e32 v36, v36
	v_fmamk_f32 v18, v18, 0x3dd53b94, v34
	v_fmamk_f32 v19, v19, 0x3dd53b94, v34
	v_fmamk_f32 v20, v20, 0x3dd53b94, v34
	v_fmamk_f32 v21, v21, 0x3dd53b94, v34
	v_fmamk_f32 v22, v22, 0x3dd53b94, v34
	v_fmamk_f32 v23, v23, 0x3dd53b94, v34
	v_fmamk_f32 v24, v24, 0x3dd53b94, v34
	v_fmamk_f32 v25, v25, 0x3dd53b94, v34
	v_fmamk_f32 v26, v26, 0x3dd53b94, v34
	v_fmamk_f32 v27, v27, 0x3dd53b94, v34
	v_fmamk_f32 v28, v28, 0x3dd53b94, v34
	v_fmamk_f32 v29, v29, 0x3dd53b94, v34
	v_fmamk_f32 v30, v30, 0x3dd53b94, v34
	v_fmamk_f32 v31, v31, 0x3dd53b94, v34
	v_fmamk_f32 v32, v32, 0x3dd53b94, v34
	v_exp_f32_e32 v82, v18
	v_exp_f32_e32 v83, v19
	v_exp_f32_e32 v84, v20
	v_exp_f32_e32 v85, v21
	v_exp_f32_e32 v184, v22
	v_exp_f32_e32 v185, v23
	v_exp_f32_e32 v182, v24
	v_exp_f32_e32 v183, v25
	v_exp_f32_e32 v144, v26
	v_exp_f32_e32 v145, v27
	v_exp_f32_e32 v138, v28
	v_exp_f32_e32 v139, v29
	v_exp_f32_e32 v142, v30
	v_exp_f32_e32 v143, v31
	v_exp_f32_e32 v140, v32
	v_exp_f32_e32 v141, v35
	s_waitcnt vmcnt(1)
	s_barrier
	s_add_u32 s34, s34, s58
	v_add_u32_e32 v2, v54, v53
	v_lshl_add_u32 v202, v56, 4, v61
	s_addc_u32 s35, s35, 0
	v_ashrrev_i32_e32 v3, 31, v2
	v_mov_b32_e32 v196, 0
	v_cndmask_b32_e64 v221, v36, 1.0, vcc
	v_pk_fma_f32 v[80:81], v[16:17], s[4:5], v[34:35] op_sel_hi:[1,0,0]
	v_pk_fma_f32 v[78:79], v[14:15], s[4:5], v[34:35] op_sel_hi:[1,0,0]
	v_pk_fma_f32 v[76:77], v[12:13], s[4:5], v[34:35] op_sel_hi:[1,0,0]
	v_pk_fma_f32 v[74:75], v[10:11], s[4:5], v[34:35] op_sel_hi:[1,0,0]
	v_pk_fma_f32 v[72:73], v[8:9], s[4:5], v[34:35] op_sel_hi:[1,0,0]
	v_pk_fma_f32 v[70:71], v[6:7], s[4:5], v[34:35] op_sel_hi:[1,0,0]
	v_pk_fma_f32 v[68:69], v[4:5], s[4:5], v[34:35] op_sel_hi:[1,0,0]
	v_add_u32_e32 v222, s43, v59
	v_add_u32_e32 v223, s43, v55
	v_cmp_gt_u32_e64 s[2:3], 32, v195
	v_lshl_add_u32 v204, v52, 2, s36
	v_lshl_add_u32 v201, v58, 4, s36
	v_add_u32_e32 v200, 0x4000, v206
	v_add_u32_e32 v199, 0x4000, v205
	v_add_u32_e32 v198, 0x4000, v203
	v_add_u32_e32 v197, 0x4000, v202
	v_lshl_add_u64 v[176:177], v[170:171], 0, v[50:51]
	v_lshl_add_u64 v[178:179], s[34:35], 0, v[174:175]
	v_lshl_add_u64 v[180:181], s[34:35], 0, v[2:3]
	s_mov_b32 s58, -1
	v_mov_b32_e32 v2, 0
	v_mov_b32_e32 v3, v196
	v_mov_b32_e32 v4, v196
	v_mov_b32_e32 v5, v196
	v_mov_b32_e32 v6, v196
	v_mov_b32_e32 v7, v196
	v_mov_b32_e32 v8, v196
	v_mov_b32_e32 v9, v196
	v_mov_b32_e32 v10, v196
	v_mov_b32_e32 v11, v196
	v_mov_b32_e32 v12, v196
	v_mov_b32_e32 v13, v196
	v_mov_b32_e32 v14, v196
	v_mov_b32_e32 v15, v196
	v_mov_b32_e32 v16, v196
	v_mov_b32_e32 v17, v196
	v_mov_b32_e32 v18, 0
	v_mov_b32_e32 v19, v196
	v_mov_b32_e32 v20, v196
	v_mov_b32_e32 v21, v196
	v_mov_b32_e32 v22, v196
	v_mov_b32_e32 v23, v196
	v_mov_b32_e32 v24, v196
	v_mov_b32_e32 v25, v196
	v_mov_b32_e32 v26, v196
	v_mov_b32_e32 v27, v196
	v_mov_b32_e32 v28, v196
	v_mov_b32_e32 v29, v196
	v_mov_b32_e32 v30, v196
	v_mov_b32_e32 v31, v196
	v_mov_b32_e32 v32, v196
	v_mov_b32_e32 v33, v196
	v_mov_b32_e32 v34, 0
	v_mov_b32_e32 v35, v196
	v_mov_b32_e32 v36, v196
	v_mov_b32_e32 v37, v196
	v_mov_b32_e32 v38, v196
	v_mov_b32_e32 v39, v196
	v_mov_b32_e32 v40, v196
	v_mov_b32_e32 v41, v196
	v_mov_b32_e32 v42, v196
	v_mov_b32_e32 v43, v196
	v_mov_b32_e32 v44, v196
	v_mov_b32_e32 v45, v196
	v_mov_b32_e32 v46, v196
	v_mov_b32_e32 v47, v196
	v_mov_b32_e32 v48, v196
	v_mov_b32_e32 v49, v196
	v_mov_b32_e32 v50, 0
	v_mov_b32_e32 v51, v196
	v_mov_b32_e32 v52, v196
	v_mov_b32_e32 v53, v196
	v_mov_b32_e32 v54, v196
	v_mov_b32_e32 v55, v196
	v_mov_b32_e32 v56, v196
	v_mov_b32_e32 v57, v196
	v_mov_b32_e32 v58, v196
	v_mov_b32_e32 v59, v196
	v_mov_b32_e32 v60, v196
	v_mov_b32_e32 v61, v196
	v_mov_b32_e32 v62, v196
	v_mov_b32_e32 v63, v196
	v_mov_b32_e32 v64, v196
	v_mov_b32_e32 v65, v196
	.p2align 6

.LBB0_1882:
	v_lshrrev_b32_e32 v4, 3, v39
	v_and_b32_e32 v3, 8, v39
	v_and_b32_e32 v56, 4, v4
	v_bfe_u32 v4, v39, 1, 2
	v_or3_b32 v3, v4, v3, v56
	v_lshlrev_b32_e32 v4, 3, v39
	v_bfe_u32 v10, v39, 1, 3
	v_lshlrev_b32_e32 v3, 7, v3
	v_and_b32_e32 v4, 8, v4
	v_and_b32_e32 v11, 1, v2
	v_add3_u32 v12, v4, s67, v3
	v_bitop3_b32 v2, v2, v10, 1 bitop3:0x6c
	v_lshl_add_u32 v194, v2, 4, v12
	v_bitop3_b32 v2, v11, v10, 2 bitop3:0x36
	v_lshlrev_b32_e32 v48, 3, v38
	v_lshl_add_u32 v193, v2, 4, v12
	v_bitop3_b32 v2, v48, v162, s37 bitop3:0x6c
	v_lshl_add_u32 v49, v38, 7, s67
	s_waitcnt lgkmcnt(0)
	v_add_u32_e32 v197, v49, v2
	v_or_b32_e32 v2, 16, v162
	s_barrier
	v_bitop3_b32 v2, v48, v2, s37 bitop3:0x6c
	v_add_u32_e32 v198, v49, v2
	ds_read_b128 v[2:5], v197 offset:32768
	ds_read_b128 v[40:43], v197 offset:36864
	ds_read_b128 v[6:9], v198 offset:32768
	ds_read_b128 v[44:47], v198 offset:36864
	v_bitop3_b32 v13, v11, v10, 4 bitop3:0x36
	v_bitop3_b32 v10, v11, v10, 6 bitop3:0x36
	v_lshl_add_u32 v192, v13, 4, v12
	v_lshl_add_u32 v190, v10, 4, v12
	s_waitcnt vmcnt(0) lgkmcnt(0)
	v_mfma_f32_32x32x64_f8f6f4 v[18:33], v[2:9], v[154:161], 0
	v_mfma_f32_32x32x64_f8f6f4 v[2:17], v[40:47], v[154:161], 0
	v_or_b32_e32 v40, 64, v162
	v_bitop3_b32 v40, v48, v40, s37 bitop3:0x6c
	v_add_u32_e32 v195, v49, v40
	v_or_b32_e32 v40, 0x50, v162
	v_bitop3_b32 v40, v48, v40, s37 bitop3:0x6c
	v_add_u32_e32 v196, v49, v40
	ds_read_b128 v[40:43], v195 offset:32768
	ds_read_b128 v[48:51], v195 offset:36864
	ds_read_b128 v[44:47], v196 offset:32768
	ds_read_b128 v[52:55], v196 offset:36864
	s_waitcnt lgkmcnt(1)
	v_mfma_f32_32x32x64_f8f6f4 v[18:33], v[40:47], v[146:153], v[18:33]
	s_waitcnt lgkmcnt(0)
	v_mfma_f32_32x32x64_f8f6f4 v[2:17], v[48:55], v[146:153], v[2:17]
	v_and_b32_e32 v181, 63, v39
	s_nop 15
	s_nop 7
	s_lshr_b32 s4, s4, 3
	v_max_f32_e32 v39, v19, v19
	v_max_f32_e32 v40, v18, v18
	v_max_f32_e32 v39, v40, v39
	v_max3_f32 v39, v39, v20, v21
	v_max3_f32 v39, v39, v22, v23
	v_max3_f32 v39, v39, v24, v25
	v_max3_f32 v39, v39, v26, v27
	v_max3_f32 v39, v39, v28, v29
	v_max3_f32 v39, v39, v30, v31
	v_max3_f32 v39, v39, v32, v33
	v_max3_f32 v39, v39, v2, v3
	v_max3_f32 v39, v39, v4, v5
	v_max3_f32 v39, v39, v6, v7
	v_max3_f32 v39, v39, v8, v9
	v_max3_f32 v39, v39, v10, v11
	v_max3_f32 v39, v39, v12, v13
	v_max3_f32 v39, v39, v14, v15
	v_max3_f32 v39, v39, v16, v17
	v_mov_b32_e32 v40, v39
	s_nop 1
	v_permlane32_swap_b32_e32 v39, v40
	v_max_f32_e32 v40, v40, v40
	v_max_f32_e32 v39, v39, v39
	v_max_f32_e32 v39, v39, v40
	s_and_b32 s30, s49, 0x3fffffc0
	v_add_f32_e32 v40, 0x7149f2ca, v39
	v_max_f32_e32 v39, 0xf149f2ca, v39
	s_lshl_b32 s30, s30, 2
	s_lshl_b32 s4, s4, 5
	v_sub_f32_e32 v41, 0xf149f2ca, v39
	s_add_i32 s30, s71, s30
	s_and_b32 s4, s4, 0x180
	v_mul_f32_e32 v41, 0x3e0293ee, v41
	v_cmp_ge_f32_e32 vcc, s38, v40
	v_exp_f32_e32 v41, v41
	s_cmp_eq_u64 vcc, exec
	s_cselect_b64 vcc, -1, 0
	s_add_u32 s2, s46, s2
	v_cndmask_b32_e32 v200, v39, v180, vcc
	s_addc_u32 s3, s47, s3
	s_add_i32 s31, s67, s48
	v_fma_f32 v40, v200, s39, 4.0
	s_add_i32 s47, s31, 0x4000
	v_pk_fma_f32 v[66:67], v[2:3], s[6:7], v[40:41] op_sel_hi:[1,0,0]
	v_lshl_add_u64 v[2:3], s[2:3], 0, v[36:37]
	s_mov_b32 m0, s47
	v_mov_b32_e32 v39, v40
	global_load_lds_dwordx4 v[2:3], off
	v_fmamk_f32 v18, v18, 0x3e0293ee, v40
	v_fmamk_f32 v19, v19, 0x3e0293ee, v40
	v_fmamk_f32 v20, v20, 0x3e0293ee, v40
	v_fmamk_f32 v21, v21, 0x3e0293ee, v40
	v_fmamk_f32 v22, v22, 0x3e0293ee, v40
	v_fmamk_f32 v23, v23, 0x3e0293ee, v40
	v_fmamk_f32 v24, v24, 0x3e0293ee, v40
	v_fmamk_f32 v25, v25, 0x3e0293ee, v40
	v_fmamk_f32 v26, v26, 0x3e0293ee, v40
	v_fmamk_f32 v27, v27, 0x3e0293ee, v40
	v_fmamk_f32 v28, v28, 0x3e0293ee, v40
	v_fmamk_f32 v29, v29, 0x3e0293ee, v40
	v_fmamk_f32 v30, v30, 0x3e0293ee, v40
	v_fmamk_f32 v31, v31, 0x3e0293ee, v40
	v_fmamk_f32 v32, v32, 0x3e0293ee, v40
	v_fmac_f32_e32 v39, 0x3e0293ee, v33
	v_exp_f32_e32 v82, v18
	v_exp_f32_e32 v83, v19
	v_exp_f32_e32 v84, v20
	v_exp_f32_e32 v85, v21
	v_exp_f32_e32 v172, v22
	v_exp_f32_e32 v173, v23
	v_exp_f32_e32 v170, v24
	v_exp_f32_e32 v171, v25
	v_exp_f32_e32 v168, v26
	v_exp_f32_e32 v169, v27
	v_exp_f32_e32 v140, v28
	v_exp_f32_e32 v141, v29
	v_exp_f32_e32 v144, v30
	v_exp_f32_e32 v145, v31
	v_exp_f32_e32 v142, v32
	v_exp_f32_e32 v143, v39
	s_waitcnt vmcnt(1)
	s_barrier
	s_add_u32 s28, s0, s28
	s_addc_u32 s29, s1, s29
	v_mov_b32_e32 v162, 0
	v_cndmask_b32_e64 v199, v41, 1.0, vcc
	v_pk_fma_f32 v[80:81], v[16:17], s[6:7], v[40:41] op_sel_hi:[1,0,0]
	v_pk_fma_f32 v[78:79], v[14:15], s[6:7], v[40:41] op_sel_hi:[1,0,0]
	v_pk_fma_f32 v[76:77], v[12:13], s[6:7], v[40:41] op_sel_hi:[1,0,0]
	v_pk_fma_f32 v[74:75], v[10:11], s[6:7], v[40:41] op_sel_hi:[1,0,0]
	v_pk_fma_f32 v[72:73], v[8:9], s[6:7], v[40:41] op_sel_hi:[1,0,0]
	v_pk_fma_f32 v[70:71], v[6:7], s[6:7], v[40:41] op_sel_hi:[1,0,0]
	v_pk_fma_f32 v[68:69], v[4:5], s[6:7], v[40:41] op_sel_hi:[1,0,0]
	v_cmp_gt_u32_e64 s[2:3], 32, v181
	v_lshl_add_u32 v191, v38, 2, s30
	v_lshl_add_u32 v189, v56, 2, s30
	v_add_u32_e32 v188, 0x4000, v194
	v_add_u32_e32 v187, 0x4000, v193
	v_add_u32_e32 v186, 0x4000, v192
	v_add_u32_e32 v185, 0x4000, v190
	v_lshl_add_u64 v[164:165], s[28:29], 0, v[36:37]
	v_lshl_add_u64 v[166:167], s[28:29], 0, v[34:35]
	s_mov_b32 s48, -1
	v_mov_b32_e32 v2, 0
	v_mov_b32_e32 v3, v162
	v_mov_b32_e32 v4, v162
	v_mov_b32_e32 v5, v162
	v_mov_b32_e32 v6, v162
	v_mov_b32_e32 v7, v162
	v_mov_b32_e32 v8, v162
	v_mov_b32_e32 v9, v162
	v_mov_b32_e32 v10, v162
	v_mov_b32_e32 v11, v162
	v_mov_b32_e32 v12, v162
	v_mov_b32_e32 v13, v162
	v_mov_b32_e32 v14, v162
	v_mov_b32_e32 v15, v162
	v_mov_b32_e32 v16, v162
	v_mov_b32_e32 v17, v162
	v_mov_b32_e32 v18, 0
	v_mov_b32_e32 v19, v162
	v_mov_b32_e32 v20, v162
	v_mov_b32_e32 v21, v162
	v_mov_b32_e32 v22, v162
	v_mov_b32_e32 v23, v162
	v_mov_b32_e32 v24, v162
	v_mov_b32_e32 v25, v162
	v_mov_b32_e32 v26, v162
	v_mov_b32_e32 v27, v162
	v_mov_b32_e32 v28, v162
	v_mov_b32_e32 v29, v162
	v_mov_b32_e32 v30, v162
	v_mov_b32_e32 v31, v162
	v_mov_b32_e32 v32, v162
	v_mov_b32_e32 v33, v162
	v_mov_b32_e32 v34, 0
	v_mov_b32_e32 v35, v162
	v_mov_b32_e32 v36, v162
	v_mov_b32_e32 v37, v162
	v_mov_b32_e32 v38, v162
	v_mov_b32_e32 v39, v162
	v_mov_b32_e32 v40, v162
	v_mov_b32_e32 v41, v162
	v_mov_b32_e32 v42, v162
	v_mov_b32_e32 v43, v162
	v_mov_b32_e32 v44, v162
	v_mov_b32_e32 v45, v162
	v_mov_b32_e32 v46, v162
	v_mov_b32_e32 v47, v162
	v_mov_b32_e32 v48, v162
	v_mov_b32_e32 v49, v162
	v_mov_b32_e32 v50, 0
	v_mov_b32_e32 v51, v162
	v_mov_b32_e32 v52, v162
	v_mov_b32_e32 v53, v162
	v_mov_b32_e32 v54, v162
	v_mov_b32_e32 v55, v162
	v_mov_b32_e32 v56, v162
	v_mov_b32_e32 v57, v162
	v_mov_b32_e32 v58, v162
	v_mov_b32_e32 v59, v162
	v_mov_b32_e32 v60, v162
	v_mov_b32_e32 v61, v162
	v_mov_b32_e32 v62, v162
	v_mov_b32_e32 v63, v162
	v_mov_b32_e32 v64, v162
	v_mov_b32_e32 v65, v162
	.p2align 6

.LBB0_1905:
	s_or_b64 exec, exec, s[0:1]
	s_movk_i32 s0, 0x57f
	ds_write_b32 v5, v7
	v_add_u32_e32 v7, 0x200, v6
	v_cmp_lt_i32_e64 s[0:1], s0, v6
	v_add_u32_e32 v5, 0x800, v5
	s_or_b64 s[10:11], s[0:1], s[10:11]
	v_mov_b32_e32 v6, v7
	s_andn2_b64 exec, exec, s[10:11]
	s_cbranch_execz .LBB0_1908
	.p2align 6

.LBB0_1915:
	s_waitcnt vmcnt(1)
	s_barrier
	s_addk_i32 s77, 0x80
	s_add_i32 s75, s83, 5
	s_cmp_ge_u32 s75, s78
	s_cbranch_scc1 .LBB0_2067
	.p2align 6

.LBB0_2224:
	s_waitcnt lgkmcnt(0)
	s_barrier
	s_setprio 1
	s_waitcnt lgkmcnt(0)
	v_mfma_f32_16x16x128_f8f6f4 v[126:129], v[26:33], v[58:65], v[126:129]
	v_mfma_f32_16x16x128_f8f6f4 v[122:125], v[18:25], v[58:65], v[122:125]
	v_mfma_f32_16x16x128_f8f6f4 v[110:113], v[26:33], v[50:57], v[110:113]
	v_mfma_f32_16x16x128_f8f6f4 v[106:109], v[18:25], v[50:57], v[106:109]
	v_mfma_f32_16x16x128_f8f6f4 v[94:97], v[26:33], v[42:49], v[94:97]
	v_mfma_f32_16x16x128_f8f6f4 v[90:93], v[18:25], v[42:49], v[90:93]
	v_mfma_f32_16x16x128_f8f6f4 v[78:81], v[26:33], v[34:41], v[78:81]
	v_mfma_f32_16x16x128_f8f6f4 v[74:77], v[18:25], v[34:41], v[74:77]
	s_setprio 0
	s_setprio 1
	v_mfma_f32_16x16x128_f8f6f4 v[118:121], v[10:17], v[58:65], v[118:121]
	v_mfma_f32_16x16x128_f8f6f4 v[114:117], v[2:9], v[58:65], v[114:117]
	v_mfma_f32_16x16x128_f8f6f4 v[102:105], v[10:17], v[50:57], v[102:105]
	v_mfma_f32_16x16x128_f8f6f4 v[98:101], v[2:9], v[50:57], v[98:101]
	v_mfma_f32_16x16x128_f8f6f4 v[86:89], v[10:17], v[42:49], v[86:89]
	v_mfma_f32_16x16x128_f8f6f4 v[82:85], v[2:9], v[42:49], v[82:85]
	v_mfma_f32_16x16x128_f8f6f4 v[70:73], v[10:17], v[34:41], v[70:73]
	v_mfma_f32_16x16x128_f8f6f4 v[66:69], v[2:9], v[34:41], v[66:69]
	s_setprio 0
	s_barrier
	v_add_u32_e32 v14, s48, v222
	v_add_u32_e32 v30, s53, v222
	ds_read_b128 v[2:5], v14
	ds_read_b128 v[6:9], v14 offset:1024
	ds_read_b128 v[10:13], v14 offset:2048
	ds_read_b128 v[14:17], v14 offset:3072
	ds_read_b128 v[18:21], v30
	ds_read_b128 v[22:25], v30 offset:1024
	ds_read_b128 v[26:29], v30 offset:2048
	ds_read_b128 v[30:33], v30 offset:3072
	s_add_u32 s28, s28, 0x530000
	s_addc_u32 s29, s29, 0
	s_mov_b32 m0, s42
	v_lshl_add_u64 v[228:229], s[28:29], 0, v[194:195]
	ds_read_b128 v[34:37], v226 offset:32768
	ds_read_b128 v[38:41], v226 offset:33792
	ds_read_b128 v[42:45], v226 offset:34816
	ds_read_b128 v[46:49], v226 offset:35840
	ds_read_b128 v[50:53], v226 offset:36864
	ds_read_b128 v[54:57], v226 offset:37888
	ds_read_b128 v[58:61], v226 offset:38912
	ds_read_b128 v[62:65], v226 offset:39936
	global_load_lds_dwordx4 v[228:229], off
	v_lshl_add_u64 v[228:229], s[28:29], 0, v[198:199]
	s_mov_b32 m0, s43
	s_nop 0
	global_load_lds_dwordx4 v[228:229], off
	s_waitcnt vmcnt(8)
	s_waitcnt lgkmcnt(0)
	s_barrier
	s_setprio 1
	s_waitcnt lgkmcnt(0)
	v_mfma_f32_16x16x128_f8f6f4 v[190:193], v[2:9], v[34:41], v[190:193]
	v_mfma_f32_16x16x128_f8f6f4 v[186:189], v[10:17], v[34:41], v[186:189]
	v_mfma_f32_16x16x128_f8f6f4 v[174:177], v[2:9], v[42:49], v[174:177]
	v_mfma_f32_16x16x128_f8f6f4 v[170:173], v[10:17], v[42:49], v[170:173]
	v_mfma_f32_16x16x128_f8f6f4 v[158:161], v[2:9], v[50:57], v[158:161]
	v_mfma_f32_16x16x128_f8f6f4 v[154:157], v[10:17], v[50:57], v[154:157]
	v_mfma_f32_16x16x128_f8f6f4 v[142:145], v[2:9], v[58:65], v[142:145]
	v_mfma_f32_16x16x128_f8f6f4 v[138:141], v[10:17], v[58:65], v[138:141]
	s_setprio 0
	s_setprio 1
	v_mfma_f32_16x16x128_f8f6f4 v[182:185], v[18:25], v[34:41], v[182:185]
	v_mfma_f32_16x16x128_f8f6f4 v[178:181], v[26:33], v[34:41], v[178:181]
	v_mfma_f32_16x16x128_f8f6f4 v[166:169], v[18:25], v[42:49], v[166:169]
	v_mfma_f32_16x16x128_f8f6f4 v[162:165], v[26:33], v[42:49], v[162:165]
	v_mfma_f32_16x16x128_f8f6f4 v[150:153], v[18:25], v[50:57], v[150:153]
	v_mfma_f32_16x16x128_f8f6f4 v[146:149], v[26:33], v[50:57], v[146:149]
	v_mfma_f32_16x16x128_f8f6f4 v[134:137], v[18:25], v[58:65], v[134:137]
	v_mfma_f32_16x16x128_f8f6f4 v[130:133], v[26:33], v[58:65], v[130:133]
	s_setprio 0
	s_barrier
	s_mov_b32 m0, s49
	v_lshl_add_u64 v[214:215], v[214:215], 0, s[14:15]
	s_add_u32 s26, s26, 0x40080
	ds_read_b128 v[34:37], v226 offset:49152
	ds_read_b128 v[38:41], v226 offset:50176
	ds_read_b128 v[42:45], v226 offset:51200
	ds_read_b128 v[46:49], v226 offset:52224
	ds_read_b128 v[50:53], v226 offset:53248
	ds_read_b128 v[54:57], v226 offset:54272
	ds_read_b128 v[58:61], v226 offset:55296
	ds_read_b128 v[62:65], v226 offset:56320
	global_load_lds_dwordx4 v[214:215], off
	v_lshl_add_u64 v[214:215], v[216:217], 0, s[14:15]
	s_mov_b32 m0, s50
	s_addc_u32 s27, s27, 0
	global_load_lds_dwordx4 v[214:215], off
	v_lshl_add_u64 v[214:215], s[26:27], 0, v[196:197]
	s_mov_b32 m0, s54
	s_nop 0
	global_load_lds_dwordx4 v[214:215], off
	v_lshl_add_u64 v[214:215], s[26:27], 0, v[200:201]
	s_mov_b32 m0, s55
	s_nop 0
	global_load_lds_dwordx4 v[214:215], off
	v_lshl_add_u64 v[214:215], v[218:219], 0, s[16:17]
	s_mov_b32 m0, s51
	s_nop 0
	global_load_lds_dwordx4 v[214:215], off
	v_lshl_add_u64 v[214:215], v[220:221], 0, s[16:17]
	s_mov_b32 m0, s52
	s_nop 0
	global_load_lds_dwordx4 v[214:215], off
	s_waitcnt vmcnt(8)
	s_waitcnt lgkmcnt(0)
	s_barrier
	s_setprio 1
	s_waitcnt lgkmcnt(0)
	v_mfma_f32_16x16x128_f8f6f4 v[126:129], v[2:9], v[34:41], v[126:129]
	v_mfma_f32_16x16x128_f8f6f4 v[122:125], v[10:17], v[34:41], v[122:125]
	v_mfma_f32_16x16x128_f8f6f4 v[110:113], v[2:9], v[42:49], v[110:113]
	v_mfma_f32_16x16x128_f8f6f4 v[106:109], v[10:17], v[42:49], v[106:109]
	v_mfma_f32_16x16x128_f8f6f4 v[94:97], v[2:9], v[50:57], v[94:97]
	v_mfma_f32_16x16x128_f8f6f4 v[90:93], v[10:17], v[50:57], v[90:93]
	v_mfma_f32_16x16x128_f8f6f4 v[78:81], v[2:9], v[58:65], v[78:81]
	v_mfma_f32_16x16x128_f8f6f4 v[74:77], v[10:17], v[58:65], v[74:77]
	s_setprio 0
	s_setprio 1
	v_mfma_f32_16x16x128_f8f6f4 v[118:121], v[18:25], v[34:41], v[118:121]
	v_mfma_f32_16x16x128_f8f6f4 v[114:117], v[26:33], v[34:41], v[114:117]
	v_mfma_f32_16x16x128_f8f6f4 v[102:105], v[18:25], v[42:49], v[102:105]
	v_mfma_f32_16x16x128_f8f6f4 v[98:101], v[26:33], v[42:49], v[98:101]
	v_mfma_f32_16x16x128_f8f6f4 v[86:89], v[18:25], v[50:57], v[86:89]
	v_mfma_f32_16x16x128_f8f6f4 v[82:85], v[26:33], v[50:57], v[82:85]
	v_mfma_f32_16x16x128_f8f6f4 v[70:73], v[18:25], v[58:65], v[70:73]
	v_mfma_f32_16x16x128_f8f6f4 v[66:69], v[26:33], v[58:65], v[66:69]
	s_setprio 0
	s_barrier
	s_add_i32 s69, s69, 2
	s_add_u32 s6, s6, 0x200
	s_addc_u32 s7, s7, 0
	s_add_u32 s67, s67, 0x100
	s_addc_u32 s68, s68, 0
	s_cmp_gt_u32 s69, 13
	s_cbranch_scc1 .LBB0_2232
	.p2align 6

.LBB0_2409:
	s_waitcnt lgkmcnt(0)
	s_barrier
	s_setprio 1
	s_waitcnt lgkmcnt(0)
	v_mfma_f32_16x16x128_f8f6f4 v[126:129], v[26:33], v[58:65], v[126:129]
	v_mfma_f32_16x16x128_f8f6f4 v[122:125], v[18:25], v[58:65], v[122:125]
	v_mfma_f32_16x16x128_f8f6f4 v[114:117], v[26:33], v[50:57], v[114:117]
	v_mfma_f32_16x16x128_f8f6f4 v[106:109], v[18:25], v[50:57], v[106:109]
	v_mfma_f32_16x16x128_f8f6f4 v[98:101], v[26:33], v[42:49], v[98:101]
	v_mfma_f32_16x16x128_f8f6f4 v[90:93], v[18:25], v[42:49], v[90:93]
	v_mfma_f32_16x16x128_f8f6f4 v[82:85], v[26:33], v[34:41], v[82:85]
	v_mfma_f32_16x16x128_f8f6f4 v[74:77], v[18:25], v[34:41], v[74:77]
	s_setprio 0
	s_setprio 1
	v_mfma_f32_16x16x128_f8f6f4 v[118:121], v[10:17], v[58:65], v[118:121]
	v_mfma_f32_16x16x128_f8f6f4 v[110:113], v[2:9], v[58:65], v[110:113]
	v_mfma_f32_16x16x128_f8f6f4 v[102:105], v[10:17], v[50:57], v[102:105]
	v_mfma_f32_16x16x128_f8f6f4 v[94:97], v[2:9], v[50:57], v[94:97]
	v_mfma_f32_16x16x128_f8f6f4 v[86:89], v[10:17], v[42:49], v[86:89]
	v_mfma_f32_16x16x128_f8f6f4 v[78:81], v[2:9], v[42:49], v[78:81]
	v_mfma_f32_16x16x128_f8f6f4 v[70:73], v[10:17], v[34:41], v[70:73]
	v_mfma_f32_16x16x128_f8f6f4 v[66:69], v[2:9], v[34:41], v[66:69]
	s_setprio 0
	s_barrier
	v_add_u32_e32 v14, s57, v222
	v_add_u32_e32 v30, s62, v222
	ds_read_b128 v[2:5], v14
	ds_read_b128 v[6:9], v14 offset:1024
	ds_read_b128 v[10:13], v14 offset:2048
	ds_read_b128 v[14:17], v14 offset:3072
	ds_read_b128 v[18:21], v30
	ds_read_b128 v[22:25], v30 offset:1024
	ds_read_b128 v[26:29], v30 offset:2048
	ds_read_b128 v[30:33], v30 offset:3072
	s_add_u32 s40, s40, 0x40000
	s_addc_u32 s41, s41, 0
	s_mov_b32 m0, s55
	v_lshl_add_u64 v[228:229], s[40:41], 0, v[194:195]
	ds_read_b128 v[34:37], v226 offset:32768
	ds_read_b128 v[38:41], v226 offset:33792
	ds_read_b128 v[42:45], v226 offset:34816
	ds_read_b128 v[46:49], v226 offset:35840
	ds_read_b128 v[50:53], v226 offset:36864
	ds_read_b128 v[54:57], v226 offset:37888
	ds_read_b128 v[58:61], v226 offset:38912
	ds_read_b128 v[62:65], v226 offset:39936
	global_load_lds_dwordx4 v[228:229], off
	v_lshl_add_u64 v[228:229], s[40:41], 0, v[198:199]
	s_mov_b32 m0, s56
	s_nop 0
	global_load_lds_dwordx4 v[228:229], off
	s_waitcnt vmcnt(8)
	s_waitcnt lgkmcnt(0)
	s_barrier
	s_setprio 1
	s_waitcnt lgkmcnt(0)
	v_mfma_f32_16x16x128_f8f6f4 v[190:193], v[2:9], v[34:41], v[190:193]
	v_mfma_f32_16x16x128_f8f6f4 v[186:189], v[10:17], v[34:41], v[186:189]
	v_mfma_f32_16x16x128_f8f6f4 v[178:181], v[2:9], v[42:49], v[178:181]
	v_mfma_f32_16x16x128_f8f6f4 v[170:173], v[10:17], v[42:49], v[170:173]
	v_mfma_f32_16x16x128_f8f6f4 v[162:165], v[2:9], v[50:57], v[162:165]
	v_mfma_f32_16x16x128_f8f6f4 v[154:157], v[10:17], v[50:57], v[154:157]
	v_mfma_f32_16x16x128_f8f6f4 v[146:149], v[2:9], v[58:65], v[146:149]
	v_mfma_f32_16x16x128_f8f6f4 v[138:141], v[10:17], v[58:65], v[138:141]
	s_setprio 0
	s_setprio 1
	v_mfma_f32_16x16x128_f8f6f4 v[182:185], v[18:25], v[34:41], v[182:185]
	v_mfma_f32_16x16x128_f8f6f4 v[174:177], v[26:33], v[34:41], v[174:177]
	v_mfma_f32_16x16x128_f8f6f4 v[166:169], v[18:25], v[42:49], v[166:169]
	v_mfma_f32_16x16x128_f8f6f4 v[158:161], v[26:33], v[42:49], v[158:161]
	v_mfma_f32_16x16x128_f8f6f4 v[150:153], v[18:25], v[50:57], v[150:153]
	v_mfma_f32_16x16x128_f8f6f4 v[142:145], v[26:33], v[50:57], v[142:145]
	v_mfma_f32_16x16x128_f8f6f4 v[134:137], v[18:25], v[58:65], v[134:137]
	v_mfma_f32_16x16x128_f8f6f4 v[130:133], v[26:33], v[58:65], v[130:133]
	s_setprio 0
	s_barrier
	s_mov_b32 m0, s58
	v_lshl_add_u64 v[214:215], v[214:215], 0, s[6:7]
	s_add_u32 s38, s38, 0x40080
	ds_read_b128 v[34:37], v226 offset:49152
	ds_read_b128 v[38:41], v226 offset:50176
	ds_read_b128 v[42:45], v226 offset:51200
	ds_read_b128 v[46:49], v226 offset:52224
	ds_read_b128 v[50:53], v226 offset:53248
	ds_read_b128 v[54:57], v226 offset:54272
	ds_read_b128 v[58:61], v226 offset:55296
	ds_read_b128 v[62:65], v226 offset:56320
	global_load_lds_dwordx4 v[214:215], off
	v_lshl_add_u64 v[214:215], v[216:217], 0, s[6:7]
	s_mov_b32 m0, s59
	s_addc_u32 s39, s39, 0
	global_load_lds_dwordx4 v[214:215], off
	v_lshl_add_u64 v[214:215], s[38:39], 0, v[196:197]
	s_mov_b32 m0, s63
	s_nop 0
	global_load_lds_dwordx4 v[214:215], off
	v_lshl_add_u64 v[214:215], s[38:39], 0, v[200:201]
	s_mov_b32 m0, s64
	s_nop 0
	global_load_lds_dwordx4 v[214:215], off
	v_lshl_add_u64 v[214:215], v[218:219], 0, s[6:7]
	s_mov_b32 m0, s60
	s_nop 0
	global_load_lds_dwordx4 v[214:215], off
	v_lshl_add_u64 v[214:215], v[220:221], 0, s[6:7]
	s_mov_b32 m0, s61
	s_nop 0
	global_load_lds_dwordx4 v[214:215], off
	s_waitcnt vmcnt(8)
	s_waitcnt lgkmcnt(0)
	s_barrier
	s_setprio 1
	s_waitcnt lgkmcnt(0)
	v_mfma_f32_16x16x128_f8f6f4 v[126:129], v[2:9], v[34:41], v[126:129]
	v_mfma_f32_16x16x128_f8f6f4 v[122:125], v[10:17], v[34:41], v[122:125]
	v_mfma_f32_16x16x128_f8f6f4 v[114:117], v[2:9], v[42:49], v[114:117]
	v_mfma_f32_16x16x128_f8f6f4 v[106:109], v[10:17], v[42:49], v[106:109]
	v_mfma_f32_16x16x128_f8f6f4 v[98:101], v[2:9], v[50:57], v[98:101]
	v_mfma_f32_16x16x128_f8f6f4 v[90:93], v[10:17], v[50:57], v[90:93]
	v_mfma_f32_16x16x128_f8f6f4 v[82:85], v[2:9], v[58:65], v[82:85]
	v_mfma_f32_16x16x128_f8f6f4 v[74:77], v[10:17], v[58:65], v[74:77]
	s_setprio 0
	s_setprio 1
	v_mfma_f32_16x16x128_f8f6f4 v[118:121], v[18:25], v[34:41], v[118:121]
	v_mfma_f32_16x16x128_f8f6f4 v[110:113], v[26:33], v[34:41], v[110:113]
	v_mfma_f32_16x16x128_f8f6f4 v[102:105], v[18:25], v[42:49], v[102:105]
	v_mfma_f32_16x16x128_f8f6f4 v[94:97], v[26:33], v[42:49], v[94:97]
	v_mfma_f32_16x16x128_f8f6f4 v[86:89], v[18:25], v[50:57], v[86:89]
	v_mfma_f32_16x16x128_f8f6f4 v[78:81], v[26:33], v[50:57], v[78:81]
	v_mfma_f32_16x16x128_f8f6f4 v[70:73], v[18:25], v[58:65], v[70:73]
	v_mfma_f32_16x16x128_f8f6f4 v[66:69], v[26:33], v[58:65], v[66:69]
	s_setprio 0
	s_barrier
	s_add_i32 s76, s76, 2
	s_add_u32 s36, s36, 0x100
	s_addc_u32 s37, s37, 0
	s_cmp_gt_u32 s76, 13
	s_cbranch_scc1 .LBB0_2417
	.p2align 6

.LBB0_2741:
	s_waitcnt lgkmcnt(0)
	s_barrier
	s_setprio 1
	s_waitcnt lgkmcnt(0)
	v_mfma_f32_16x16x32_bf16 v[62:65], v[146:149], v[186:189], v[62:65]
	v_mfma_f32_16x16x32_bf16 v[58:61], v[154:157], v[186:189], v[58:61]
	v_mfma_f32_16x16x32_bf16 v[54:57], v[146:149], v[178:181], v[54:57]
	v_mfma_f32_16x16x32_bf16 v[46:49], v[154:157], v[178:181], v[46:49]
	v_mfma_f32_16x16x32_bf16 v[38:41], v[146:149], v[170:173], v[38:41]
	v_mfma_f32_16x16x32_bf16 v[30:33], v[154:157], v[170:173], v[30:33]
	v_mfma_f32_16x16x32_bf16 v[22:25], v[146:149], v[162:165], v[22:25]
	v_mfma_f32_16x16x32_bf16 v[14:17], v[154:157], v[162:165], v[14:17]
	v_mfma_f32_16x16x32_bf16 v[62:65], v[150:153], v[190:193], v[62:65]
	v_mfma_f32_16x16x32_bf16 v[58:61], v[158:161], v[190:193], v[58:61]
	v_mfma_f32_16x16x32_bf16 v[54:57], v[150:153], v[182:185], v[54:57]
	v_mfma_f32_16x16x32_bf16 v[46:49], v[158:161], v[182:185], v[46:49]
	v_mfma_f32_16x16x32_bf16 v[38:41], v[150:153], v[174:177], v[38:41]
	v_mfma_f32_16x16x32_bf16 v[30:33], v[158:161], v[174:177], v[30:33]
	v_mfma_f32_16x16x32_bf16 v[22:25], v[150:153], v[166:169], v[22:25]
	v_mfma_f32_16x16x32_bf16 v[14:17], v[158:161], v[166:169], v[14:17]
	s_setprio 0
	s_setprio 1
	v_mfma_f32_16x16x32_bf16 v[50:53], v[130:133], v[186:189], v[50:53]
	v_mfma_f32_16x16x32_bf16 v[42:45], v[138:141], v[186:189], v[42:45]
	v_mfma_f32_16x16x32_bf16 v[34:37], v[130:133], v[178:181], v[34:37]
	v_mfma_f32_16x16x32_bf16 v[26:29], v[138:141], v[178:181], v[26:29]
	v_mfma_f32_16x16x32_bf16 v[18:21], v[130:133], v[170:173], v[18:21]
	v_mfma_f32_16x16x32_bf16 v[10:13], v[138:141], v[170:173], v[10:13]
	v_mfma_f32_16x16x32_bf16 v[6:9], v[130:133], v[162:165], v[6:9]
	v_mfma_f32_16x16x32_bf16 v[2:5], v[138:141], v[162:165], v[2:5]
	v_mfma_f32_16x16x32_bf16 v[50:53], v[134:137], v[190:193], v[50:53]
	v_mfma_f32_16x16x32_bf16 v[42:45], v[142:145], v[190:193], v[42:45]
	v_mfma_f32_16x16x32_bf16 v[34:37], v[134:137], v[182:185], v[34:37]
	v_mfma_f32_16x16x32_bf16 v[26:29], v[142:145], v[182:185], v[26:29]
	v_mfma_f32_16x16x32_bf16 v[18:21], v[134:137], v[174:177], v[18:21]
	v_mfma_f32_16x16x32_bf16 v[10:13], v[142:145], v[174:177], v[10:13]
	v_mfma_f32_16x16x32_bf16 v[6:9], v[134:137], v[166:169], v[6:9]
	v_mfma_f32_16x16x32_bf16 v[2:5], v[142:145], v[166:169], v[2:5]
	s_setprio 0
	s_barrier
	v_add_u32_e32 v142, s48, v222
	v_add_u32_e32 v158, s53, v222
	ds_read_b128 v[130:133], v142
	ds_read_b128 v[134:137], v142 offset:1024
	ds_read_b128 v[138:141], v142 offset:2048
	ds_read_b128 v[142:145], v142 offset:3072
	ds_read_b128 v[146:149], v158
	ds_read_b128 v[150:153], v158 offset:1024
	ds_read_b128 v[154:157], v158 offset:2048
	ds_read_b128 v[158:161], v158 offset:3072
	s_add_u32 s30, s30, 0x160000
	s_addc_u32 s31, s31, 0
	s_mov_b32 m0, s46
	v_lshl_add_u64 v[228:229], s[30:31], 0, v[194:195]
	ds_read_b128 v[162:165], v226 offset:32768
	ds_read_b128 v[166:169], v226 offset:33792
	ds_read_b128 v[170:173], v226 offset:34816
	ds_read_b128 v[174:177], v226 offset:35840
	ds_read_b128 v[178:181], v226 offset:36864
	ds_read_b128 v[182:185], v226 offset:37888
	ds_read_b128 v[186:189], v226 offset:38912
	ds_read_b128 v[190:193], v226 offset:39936
	global_load_lds_dwordx4 v[228:229], off
	v_lshl_add_u64 v[228:229], s[30:31], 0, v[198:199]
	s_mov_b32 m0, s47
	s_nop 0
	global_load_lds_dwordx4 v[228:229], off
	s_waitcnt vmcnt(8)
	s_waitcnt lgkmcnt(0)
	s_barrier
	s_setprio 1
	s_waitcnt lgkmcnt(0)
	v_mfma_f32_16x16x32_bf16 v[126:129], v[130:133], v[162:165], v[126:129]
	v_mfma_f32_16x16x32_bf16 v[122:125], v[138:141], v[162:165], v[122:125]
	v_mfma_f32_16x16x32_bf16 v[118:121], v[130:133], v[170:173], v[118:121]
	v_mfma_f32_16x16x32_bf16 v[110:113], v[138:141], v[170:173], v[110:113]
	v_mfma_f32_16x16x32_bf16 v[102:105], v[130:133], v[178:181], v[102:105]
	v_mfma_f32_16x16x32_bf16 v[94:97], v[138:141], v[178:181], v[94:97]
	v_mfma_f32_16x16x32_bf16 v[86:89], v[130:133], v[186:189], v[86:89]
	v_mfma_f32_16x16x32_bf16 v[78:81], v[138:141], v[186:189], v[78:81]
	v_mfma_f32_16x16x32_bf16 v[126:129], v[134:137], v[166:169], v[126:129]
	v_mfma_f32_16x16x32_bf16 v[122:125], v[142:145], v[166:169], v[122:125]
	v_mfma_f32_16x16x32_bf16 v[118:121], v[134:137], v[174:177], v[118:121]
	v_mfma_f32_16x16x32_bf16 v[110:113], v[142:145], v[174:177], v[110:113]
	v_mfma_f32_16x16x32_bf16 v[102:105], v[134:137], v[182:185], v[102:105]
	v_mfma_f32_16x16x32_bf16 v[94:97], v[142:145], v[182:185], v[94:97]
	v_mfma_f32_16x16x32_bf16 v[86:89], v[134:137], v[190:193], v[86:89]
	v_mfma_f32_16x16x32_bf16 v[78:81], v[142:145], v[190:193], v[78:81]
	s_setprio 0
	s_setprio 1
	v_mfma_f32_16x16x32_bf16 v[114:117], v[146:149], v[162:165], v[114:117]
	v_mfma_f32_16x16x32_bf16 v[106:109], v[154:157], v[162:165], v[106:109]
	v_mfma_f32_16x16x32_bf16 v[98:101], v[146:149], v[170:173], v[98:101]
	v_mfma_f32_16x16x32_bf16 v[90:93], v[154:157], v[170:173], v[90:93]
	v_mfma_f32_16x16x32_bf16 v[82:85], v[146:149], v[178:181], v[82:85]
	v_mfma_f32_16x16x32_bf16 v[74:77], v[154:157], v[178:181], v[74:77]
	v_mfma_f32_16x16x32_bf16 v[70:73], v[146:149], v[186:189], v[70:73]
	v_mfma_f32_16x16x32_bf16 v[66:69], v[154:157], v[186:189], v[66:69]
	v_mfma_f32_16x16x32_bf16 v[114:117], v[150:153], v[166:169], v[114:117]
	v_mfma_f32_16x16x32_bf16 v[106:109], v[158:161], v[166:169], v[106:109]
	v_mfma_f32_16x16x32_bf16 v[98:101], v[150:153], v[174:177], v[98:101]
	v_mfma_f32_16x16x32_bf16 v[90:93], v[158:161], v[174:177], v[90:93]
	v_mfma_f32_16x16x32_bf16 v[82:85], v[150:153], v[182:185], v[82:85]
	v_mfma_f32_16x16x32_bf16 v[74:77], v[158:161], v[182:185], v[74:77]
	v_mfma_f32_16x16x32_bf16 v[70:73], v[150:153], v[190:193], v[70:73]
	v_mfma_f32_16x16x32_bf16 v[66:69], v[158:161], v[190:193], v[66:69]
	s_setprio 0
	s_barrier
	s_mov_b32 m0, s49
	v_lshl_add_u64 v[214:215], v[214:215], 0, s[8:9]
	s_add_u32 s28, s28, 0x160080
	ds_read_b128 v[162:165], v226 offset:49152
	ds_read_b128 v[166:169], v226 offset:50176
	ds_read_b128 v[170:173], v226 offset:51200
	ds_read_b128 v[174:177], v226 offset:52224
	ds_read_b128 v[178:181], v226 offset:53248
	ds_read_b128 v[182:185], v226 offset:54272
	ds_read_b128 v[186:189], v226 offset:55296
	ds_read_b128 v[190:193], v226 offset:56320
	global_load_lds_dwordx4 v[214:215], off
	v_lshl_add_u64 v[214:215], v[216:217], 0, s[8:9]
	s_mov_b32 m0, s50
	s_addc_u32 s29, s29, 0
	global_load_lds_dwordx4 v[214:215], off
	v_lshl_add_u64 v[214:215], s[28:29], 0, v[196:197]
	s_mov_b32 m0, s54
	s_nop 0
	global_load_lds_dwordx4 v[214:215], off
	v_lshl_add_u64 v[214:215], s[28:29], 0, v[200:201]
	s_mov_b32 m0, s55
	s_nop 0
	global_load_lds_dwordx4 v[214:215], off
	v_lshl_add_u64 v[214:215], v[218:219], 0, s[8:9]
	s_mov_b32 m0, s51
	s_nop 0
	global_load_lds_dwordx4 v[214:215], off
	v_lshl_add_u64 v[214:215], v[220:221], 0, s[8:9]
	s_mov_b32 m0, s52
	s_nop 0
	global_load_lds_dwordx4 v[214:215], off
	s_waitcnt vmcnt(8)
	s_waitcnt lgkmcnt(0)
	s_barrier
	s_setprio 1
	s_waitcnt lgkmcnt(0)
	v_mfma_f32_16x16x32_bf16 v[62:65], v[130:133], v[162:165], v[62:65]
	v_mfma_f32_16x16x32_bf16 v[58:61], v[138:141], v[162:165], v[58:61]
	v_mfma_f32_16x16x32_bf16 v[54:57], v[130:133], v[170:173], v[54:57]
	v_mfma_f32_16x16x32_bf16 v[46:49], v[138:141], v[170:173], v[46:49]
	v_mfma_f32_16x16x32_bf16 v[38:41], v[130:133], v[178:181], v[38:41]
	v_mfma_f32_16x16x32_bf16 v[30:33], v[138:141], v[178:181], v[30:33]
	v_mfma_f32_16x16x32_bf16 v[22:25], v[130:133], v[186:189], v[22:25]
	v_mfma_f32_16x16x32_bf16 v[14:17], v[138:141], v[186:189], v[14:17]
	v_mfma_f32_16x16x32_bf16 v[62:65], v[134:137], v[166:169], v[62:65]
	v_mfma_f32_16x16x32_bf16 v[58:61], v[142:145], v[166:169], v[58:61]
	v_mfma_f32_16x16x32_bf16 v[54:57], v[134:137], v[174:177], v[54:57]
	v_mfma_f32_16x16x32_bf16 v[46:49], v[142:145], v[174:177], v[46:49]
	v_mfma_f32_16x16x32_bf16 v[38:41], v[134:137], v[182:185], v[38:41]
	v_mfma_f32_16x16x32_bf16 v[30:33], v[142:145], v[182:185], v[30:33]
	v_mfma_f32_16x16x32_bf16 v[22:25], v[134:137], v[190:193], v[22:25]
	v_mfma_f32_16x16x32_bf16 v[14:17], v[142:145], v[190:193], v[14:17]
	s_setprio 0
	s_setprio 1
	v_mfma_f32_16x16x32_bf16 v[50:53], v[146:149], v[162:165], v[50:53]
	v_mfma_f32_16x16x32_bf16 v[42:45], v[154:157], v[162:165], v[42:45]
	v_mfma_f32_16x16x32_bf16 v[34:37], v[146:149], v[170:173], v[34:37]
	v_mfma_f32_16x16x32_bf16 v[26:29], v[154:157], v[170:173], v[26:29]
	v_mfma_f32_16x16x32_bf16 v[18:21], v[146:149], v[178:181], v[18:21]
	v_mfma_f32_16x16x32_bf16 v[10:13], v[154:157], v[178:181], v[10:13]
	v_mfma_f32_16x16x32_bf16 v[6:9], v[146:149], v[186:189], v[6:9]
	v_mfma_f32_16x16x32_bf16 v[2:5], v[154:157], v[186:189], v[2:5]
	v_mfma_f32_16x16x32_bf16 v[50:53], v[150:153], v[166:169], v[50:53]
	v_mfma_f32_16x16x32_bf16 v[42:45], v[158:161], v[166:169], v[42:45]
	v_mfma_f32_16x16x32_bf16 v[34:37], v[150:153], v[174:177], v[34:37]
	v_mfma_f32_16x16x32_bf16 v[26:29], v[158:161], v[174:177], v[26:29]
	v_mfma_f32_16x16x32_bf16 v[18:21], v[150:153], v[182:185], v[18:21]
	v_mfma_f32_16x16x32_bf16 v[10:13], v[158:161], v[182:185], v[10:13]
	v_mfma_f32_16x16x32_bf16 v[6:9], v[150:153], v[190:193], v[6:9]
	v_mfma_f32_16x16x32_bf16 v[2:5], v[158:161], v[190:193], v[2:5]
	s_setprio 0
	s_barrier
	s_add_i32 s69, s69, 2
	s_add_u32 s26, s26, 0x100
	s_addc_u32 s27, s27, 0
	s_cmpk_gt_u32 s69, 0x55
	s_cbranch_scc1 .LBB0_2749
	.p2align 6
